# adds transpose-tile loops issuing both global loads before the first wait (16 loop copies), on top of RWKV scan rewrite and S5 inner-loop reschedule
# speedup vs baseline: 1.0080x; 1.0038x over previous
; DI unsigned pack2(float a, float b) { f32v2 v = {a, b}; return __builtin_bit_cast(unsigned, __builtin_convertvector(v, bf16v2)); }
;     ...
; #pragma unroll
;     for (int r = 0; r < 2; ++r) {
;       const int e = tid + r * 512, i = e >> 4, j4 = (e & 15) * 4;
;       float4 v = make_float4(0.f, 0.f, 0.f, 0.f);
;       const int sn0 = upmap ? ((n0 & 255) >> 7) * DFF + (n0 >> 8) * 128 + (n0 & 127) : n0;
;       if (n0 + j4 < N) v = *reinterpret_cast<const float4*>(src + (size_t)(k0 + i) * N + sn0 + j4);
;       tile[i * 65 + j4] = v.x; tile[i * 65 + j4 + 1] = v.y; tile[i * 65 + j4 + 2] = v.z; tile[i * 65 + j4 + 3] = v.w;
;     }
;     __syncthreads();
;     {
;       const int jn = tid >> 3, seg = tid & 7;
;       const float* tp = tile + (seg * 8) * 65 + jn;
;       uint4 o;
;       o.x = pack2(tp[0], tp[65]); o.y = pack2(tp[2 * 65], tp[3 * 65]); o.z = pack2(tp[4 * 65], tp[5 * 65]); o.w = pack2(tp[6 * 65], tp[7 * 65]);
.LBB0_30:
	s_or_b64 exec, exec, s[12:13]
	v_lshl_add_u32 v6, v1, 2, 16
	v_mad_u64_u32 v[10:11], s[12:13], v7, s47, v[6:7]
	v_add_u32_e32 v1, 0x200, v8
	v_ashrrev_i32_e32 v24, 4, v1
	v_mov_b32_e32 v20, 0
	v_mov_b32_e32 v21, 0
	v_mov_b32_e32 v22, 0
	v_mov_b32_e32 v23, 0
	s_and_saveexec_b64 s[12:13], vcc
	s_cbranch_execz .LBB0_32
	s_lshl_b32 s9, s18, 10
	v_subrev_u32_e32 v20, s9, v24
	v_add_u32_e32 v22, s15, v20
	v_mov_b64_e32 v[20:21], s[4:5]
	s_movk_i32 s9, 0x2a00
	v_mad_i64_i32 v[20:21], s[20:21], v22, s9, v[20:21]
	s_ashr_i32 s9, s8, 31
	v_lshl_add_u64 v[20:21], s[8:9], 2, v[20:21]
	v_lshl_add_u64 v[20:21], v[20:21], 0, v[16:17]
	global_load_dwordx4 v[20:23], v[20:21], off
.LBB0_32:
	s_or_b64 exec, exec, s[12:13]
	s_waitcnt vmcnt(1)
	ds_write2_b32 v10, v2, v3 offset1:1
	ds_write2_b32 v10, v4, v5 offset0:2 offset1:3
	v_mad_u64_u32 v[4:5], s[12:13], v24, s47, v[6:7]
	s_waitcnt vmcnt(0)
	ds_write2_b32 v4, v20, v21 offset1:1
	ds_write2_b32 v4, v22, v23 offset0:2 offset1:3
	v_lshlrev_b32_e32 v0, 3, v8
	v_ashrrev_i32_e32 v10, 3, v8
	v_and_b32_e32 v9, 56, v0
	v_mul_u32_u24_e32 v0, 0x104, v9
	v_lshlrev_b32_e32 v1, 2, v10
	v_add3_u32 v4, 16, v0, v1
	v_add_u32_e32 v6, 0x400, v4
	s_waitcnt lgkmcnt(0)
	s_barrier
	ds_read2_b32 v[0:1], v4 offset1:65
	ds_read2_b32 v[2:3], v4 offset0:130 offset1:195
	ds_read2_b32 v[4:5], v6 offset0:4 offset1:69
	ds_read2_b32 v[6:7], v6 offset0:134 offset1:199
	s_cmpk_gt_i32 s14, 0xff
	s_cbranch_scc1 .LBB0_27
	v_lshrrev_b32_e32 v11, 3, v8
	v_lshrrev_b32_e32 v12, 2, v8
	v_ashrrev_i32_e32 v8, 6, v8
	v_and_b32_e32 v12, 32, v12
	v_and_b32_e32 v8, -4, v8
	v_lshlrev_b32_e32 v10, 1, v10
	v_add_u32_e32 v8, v8, v12
	v_and_b32_e32 v10, 24, v10
	v_and_or_b32 v8, v11, 3, v8
	v_add_u32_e32 v10, v8, v10
	s_branch .LBB0_27

;     ...
; #pragma unroll
;     for (int r = 0; r < 2; ++r) {
;       const int e = tid + r * 512, i = e >> 4, j4 = (e & 15) * 4;
;       float4 v = make_float4(0.f, 0.f, 0.f, 0.f);
;       const int sn0 = upmap ? ((n0 & 255) >> 7) * DFF + (n0 >> 8) * 128 + (n0 & 127) : n0;
;       if (n0 + j4 < N) v = *reinterpret_cast<const float4*>(src + (size_t)(k0 + i) * N + sn0 + j4);
;       tile[i * 65 + j4] = v.x; tile[i * 65 + j4 + 1] = v.y; tile[i * 65 + j4 + 2] = v.z; tile[i * 65 + j4 + 3] = v.w;
;     }
;     __syncthreads();
.LBB0_41:
	s_or_b64 exec, exec, s[14:15]
	v_lshl_add_u32 v6, v1, 2, 16
	v_mad_u64_u32 v[10:11], s[14:15], v7, s47, v[6:7]
	v_add_u32_e32 v1, 0x200, v8
	v_ashrrev_i32_e32 v24, 4, v1
	v_mov_b32_e32 v20, 0
	v_mov_b32_e32 v21, 0
	v_mov_b32_e32 v22, 0
	v_mov_b32_e32 v23, 0
	s_and_saveexec_b64 s[14:15], vcc
	s_cbranch_execz .LBB0_43
	v_add_u32_e32 v20, s8, v24
	v_ashrrev_i32_e32 v21, 31, v20
	v_lshlrev_b64 v[20:21], 12, v[20:21]
	v_lshl_add_u64 v[20:21], s[2:3], 0, v[20:21]
	s_ashr_i32 s13, s12, 31
	v_lshl_add_u64 v[20:21], s[12:13], 2, v[20:21]
	v_lshl_add_u64 v[20:21], v[20:21], 0, v[16:17]
	global_load_dwordx4 v[20:23], v[20:21], off
.LBB0_43:
	s_or_b64 exec, exec, s[14:15]
	s_waitcnt vmcnt(1)
	ds_write2_b32 v10, v2, v3 offset1:1
	ds_write2_b32 v10, v4, v5 offset0:2 offset1:3
	v_mad_u64_u32 v[4:5], s[14:15], v24, s47, v[6:7]
	s_waitcnt vmcnt(0)
	ds_write2_b32 v4, v20, v21 offset1:1
	ds_write2_b32 v4, v22, v23 offset0:2 offset1:3
	v_lshlrev_b32_e32 v0, 3, v8
	v_ashrrev_i32_e32 v10, 3, v8
	v_and_b32_e32 v9, 56, v0
	v_mul_u32_u24_e32 v0, 0x104, v9
	v_lshlrev_b32_e32 v1, 2, v10
	v_add3_u32 v4, 16, v0, v1
	v_add_u32_e32 v6, 0x400, v4
	s_waitcnt lgkmcnt(0)
	s_barrier
	ds_read2_b32 v[0:1], v4 offset1:65
	ds_read2_b32 v[2:3], v4 offset0:130 offset1:195
	ds_read2_b32 v[4:5], v6 offset0:4 offset1:69
	ds_read2_b32 v[6:7], v6 offset0:134 offset1:199
	s_cmpk_gt_i32 s18, 0x2b0
	s_cbranch_scc1 .LBB0_38
	v_lshrrev_b32_e32 v11, 3, v8
	v_lshrrev_b32_e32 v12, 2, v8
	v_ashrrev_i32_e32 v8, 6, v8
	v_and_b32_e32 v12, 32, v12
	v_and_b32_e32 v8, -4, v8
	v_lshlrev_b32_e32 v10, 1, v10
	v_add_u32_e32 v8, v8, v12
	v_and_b32_e32 v10, 24, v10
	v_and_or_b32 v8, v11, 3, v8
	v_add_u32_e32 v10, v8, v10
	s_branch .LBB0_38

;     ...
; #pragma unroll
;     for (int r = 0; r < 2; ++r) {
;       const int e = tid + r * 512, i = e >> 4, j4 = (e & 15) * 4;
;       float4 v = make_float4(0.f, 0.f, 0.f, 0.f);
;       const int sn0 = upmap ? ((n0 & 255) >> 7) * DFF + (n0 >> 8) * 128 + (n0 & 127) : n0;
;       if (n0 + j4 < N) v = *reinterpret_cast<const float4*>(src + (size_t)(k0 + i) * N + sn0 + j4);
;       tile[i * 65 + j4] = v.x; tile[i * 65 + j4 + 1] = v.y; tile[i * 65 + j4 + 2] = v.z; tile[i * 65 + j4 + 3] = v.w;
;     }
;     __syncthreads();
.LBB0_54:
	s_or_b64 exec, exec, s[14:15]
	s_waitcnt vmcnt(1)
	ds_write2_b32 v10, v2, v3 offset1:1
	ds_write2_b32 v10, v4, v5 offset0:2 offset1:3
	v_mad_u64_u32 v[4:5], s[14:15], v24, s47, v[6:7]
	s_waitcnt vmcnt(0)
	ds_write2_b32 v4, v20, v21 offset1:1
	ds_write2_b32 v4, v22, v23 offset0:2 offset1:3
	v_lshlrev_b32_e32 v0, 3, v8
	v_ashrrev_i32_e32 v10, 3, v8
	v_and_b32_e32 v9, 56, v0
	v_mul_u32_u24_e32 v0, 0x104, v9
	v_lshlrev_b32_e32 v1, 2, v10
	v_add3_u32 v4, 16, v0, v1
	v_add_u32_e32 v6, 0x400, v4
	s_waitcnt lgkmcnt(0)
	s_barrier
	ds_read2_b32 v[0:1], v4 offset1:65
	ds_read2_b32 v[2:3], v4 offset0:130 offset1:195
	ds_read2_b32 v[4:5], v6 offset0:4 offset1:69
	ds_read2_b32 v[6:7], v6 offset0:134 offset1:199
	s_cmpk_gt_i32 s18, 0x3b0
	s_cbranch_scc1 .LBB0_49
	v_lshrrev_b32_e32 v11, 3, v8
	v_lshrrev_b32_e32 v12, 2, v8
	v_ashrrev_i32_e32 v8, 6, v8
	v_and_b32_e32 v12, 32, v12
	v_and_b32_e32 v8, -4, v8
	v_lshlrev_b32_e32 v10, 1, v10
	v_add_u32_e32 v8, v8, v12
	v_and_b32_e32 v10, 24, v10
	v_and_or_b32 v8, v11, 3, v8
	v_add_u32_e32 v10, v8, v10
	s_branch .LBB0_49

;     ...
; #pragma unroll
;     for (int r = 0; r < 2; ++r) {
;       const int e = tid + r * 512, i = e >> 4, j4 = (e & 15) * 4;
;       float4 v = make_float4(0.f, 0.f, 0.f, 0.f);
;       const int sn0 = upmap ? ((n0 & 255) >> 7) * DFF + (n0 >> 8) * 128 + (n0 & 127) : n0;
;       if (n0 + j4 < N) v = *reinterpret_cast<const float4*>(src + (size_t)(k0 + i) * N + sn0 + j4);
;       tile[i * 65 + j4] = v.x; tile[i * 65 + j4 + 1] = v.y; tile[i * 65 + j4 + 2] = v.z; tile[i * 65 + j4 + 3] = v.w;
;     }
;     __syncthreads();
.LBB0_63:
	s_or_b64 exec, exec, s[14:15]
	v_lshl_add_u32 v6, v1, 2, 16
	v_mad_u64_u32 v[10:11], s[14:15], v7, s47, v[6:7]
	v_add_u32_e32 v1, 0x200, v8
	v_ashrrev_i32_e32 v24, 4, v1
	v_mov_b32_e32 v20, 0
	v_mov_b32_e32 v21, 0
	v_mov_b32_e32 v22, 0
	v_mov_b32_e32 v23, 0
	s_and_saveexec_b64 s[14:15], vcc
	s_cbranch_execz .LBB0_65
	v_add_u32_e32 v20, s8, v24
	v_ashrrev_i32_e32 v21, 31, v20
	v_lshlrev_b64 v[20:21], 13, v[20:21]
	v_lshl_add_u64 v[20:21], s[2:3], 0, v[20:21]
	s_ashr_i32 s13, s12, 31
	v_lshl_add_u64 v[20:21], s[12:13], 2, v[20:21]
	v_lshl_add_u64 v[20:21], v[20:21], 0, v[16:17]
	global_load_dwordx4 v[20:23], v[20:21], off
.LBB0_65:
	s_or_b64 exec, exec, s[14:15]
	s_waitcnt vmcnt(1)
	ds_write2_b32 v10, v2, v3 offset1:1
	ds_write2_b32 v10, v4, v5 offset0:2 offset1:3
	v_mad_u64_u32 v[4:5], s[14:15], v24, s47, v[6:7]
	s_waitcnt vmcnt(0)
	ds_write2_b32 v4, v20, v21 offset1:1
	ds_write2_b32 v4, v22, v23 offset0:2 offset1:3
	v_lshlrev_b32_e32 v0, 3, v8
	v_ashrrev_i32_e32 v10, 3, v8
	v_and_b32_e32 v9, 56, v0
	v_mul_u32_u24_e32 v0, 0x104, v9
	v_lshlrev_b32_e32 v1, 2, v10
	v_add3_u32 v4, 16, v0, v1
	v_add_u32_e32 v6, 0x400, v4
	s_waitcnt lgkmcnt(0)
	s_barrier
	ds_read2_b32 v[0:1], v4 offset1:65
	ds_read2_b32 v[2:3], v4 offset0:130 offset1:195
	ds_read2_b32 v[4:5], v6 offset0:4 offset1:69
	ds_read2_b32 v[6:7], v6 offset0:134 offset1:199
	s_cmpk_gt_i32 s18, 0x4b0
	s_cbranch_scc1 .LBB0_60
	v_lshrrev_b32_e32 v11, 3, v8
	v_lshrrev_b32_e32 v12, 2, v8
	v_ashrrev_i32_e32 v8, 6, v8
	v_and_b32_e32 v12, 32, v12
	v_and_b32_e32 v8, -4, v8
	v_lshlrev_b32_e32 v10, 1, v10
	v_add_u32_e32 v8, v8, v12
	v_and_b32_e32 v10, 24, v10
	v_and_or_b32 v8, v11, 3, v8
	v_add_u32_e32 v10, v8, v10
	s_branch .LBB0_60

;     ...
; #pragma unroll
;     for (int r = 0; r < 2; ++r) {
;       const int e = tid + r * 512, i = e >> 4, j4 = (e & 15) * 4;
;       float4 v = make_float4(0.f, 0.f, 0.f, 0.f);
;       const int sn0 = upmap ? ((n0 & 255) >> 7) * DFF + (n0 >> 8) * 128 + (n0 & 127) : n0;
;       if (n0 + j4 < N) v = *reinterpret_cast<const float4*>(src + (size_t)(k0 + i) * N + sn0 + j4);
;       tile[i * 65 + j4] = v.x; tile[i * 65 + j4 + 1] = v.y; tile[i * 65 + j4 + 2] = v.z; tile[i * 65 + j4 + 3] = v.w;
;     }
;     __syncthreads();
.LBB0_76:
	s_or_b64 exec, exec, s[14:15]
	s_waitcnt vmcnt(1)
	ds_write2_b32 v10, v2, v3 offset1:1
	ds_write2_b32 v10, v4, v5 offset0:2 offset1:3
	v_mad_u64_u32 v[4:5], s[14:15], v24, s47, v[6:7]
	s_waitcnt vmcnt(0)
	ds_write2_b32 v4, v20, v21 offset1:1
	ds_write2_b32 v4, v22, v23 offset0:2 offset1:3
	v_lshlrev_b32_e32 v0, 3, v8
	v_ashrrev_i32_e32 v10, 3, v8
	v_and_b32_e32 v9, 56, v0
	v_mul_u32_u24_e32 v0, 0x104, v9
	v_lshlrev_b32_e32 v1, 2, v10
	v_add3_u32 v4, 16, v0, v1
	v_add_u32_e32 v6, 0x400, v4
	s_waitcnt lgkmcnt(0)
	s_barrier
	ds_read2_b32 v[0:1], v4 offset1:65
	ds_read2_b32 v[2:3], v4 offset0:130 offset1:195
	ds_read2_b32 v[4:5], v6 offset0:4 offset1:69
	ds_read2_b32 v[6:7], v6 offset0:134 offset1:199
	s_cmpk_gt_i32 s18, 0x6b0
	s_cbranch_scc1 .LBB0_71
	v_lshrrev_b32_e32 v11, 3, v8
	v_lshrrev_b32_e32 v12, 2, v8
	v_ashrrev_i32_e32 v8, 6, v8
	v_and_b32_e32 v12, 32, v12
	v_and_b32_e32 v8, -4, v8
	v_lshlrev_b32_e32 v10, 1, v10
	v_add_u32_e32 v8, v8, v12
	v_and_b32_e32 v10, 24, v10
	v_and_or_b32 v8, v11, 3, v8
	v_add_u32_e32 v10, v8, v10
	s_branch .LBB0_71

;     ...
; #pragma unroll
;     for (int r = 0; r < 2; ++r) {
;       const int e = tid + r * 512, i = e >> 4, j4 = (e & 15) * 4;
;       float4 v = make_float4(0.f, 0.f, 0.f, 0.f);
;       const int sn0 = upmap ? ((n0 & 255) >> 7) * DFF + (n0 >> 8) * 128 + (n0 & 127) : n0;
;       if (n0 + j4 < N) v = *reinterpret_cast<const float4*>(src + (size_t)(k0 + i) * N + sn0 + j4);
;       tile[i * 65 + j4] = v.x; tile[i * 65 + j4 + 1] = v.y; tile[i * 65 + j4 + 2] = v.z; tile[i * 65 + j4 + 3] = v.w;
;     }
;     __syncthreads();
.LBB0_85:
	s_or_b64 exec, exec, s[14:15]
	v_lshl_add_u32 v6, v1, 2, 16
	v_mad_u64_u32 v[10:11], s[14:15], v7, s47, v[6:7]
	v_add_u32_e32 v1, 0x200, v8
	v_ashrrev_i32_e32 v24, 4, v1
	v_mov_b32_e32 v20, 0
	v_mov_b32_e32 v21, 0
	v_mov_b32_e32 v22, 0
	v_mov_b32_e32 v23, 0
	s_and_saveexec_b64 s[14:15], vcc
	s_cbranch_execz .LBB0_87
	v_add_u32_e32 v22, s8, v24
	v_mov_b64_e32 v[20:21], s[2:3]
	s_movk_i32 s13, 0x5800
	v_mad_i64_i32 v[20:21], s[18:19], v22, s13, v[20:21]
	s_ashr_i32 s13, s12, 31
	v_lshl_add_u64 v[20:21], s[12:13], 2, v[20:21]
	v_lshl_add_u64 v[20:21], v[20:21], 0, v[16:17]
	global_load_dwordx4 v[20:23], v[20:21], off
.LBB0_87:
	s_or_b64 exec, exec, s[14:15]
	s_waitcnt vmcnt(1)
	ds_write2_b32 v10, v2, v3 offset1:1
	ds_write2_b32 v10, v4, v5 offset0:2 offset1:3
	v_mad_u64_u32 v[4:5], s[12:13], v24, s47, v[6:7]
	s_waitcnt vmcnt(0)
	ds_write2_b32 v4, v20, v21 offset1:1
	ds_write2_b32 v4, v22, v23 offset0:2 offset1:3
	v_lshlrev_b32_e32 v0, 3, v8
	v_ashrrev_i32_e32 v10, 3, v8
	v_and_b32_e32 v9, 56, v0
	v_mul_u32_u24_e32 v0, 0x104, v9
	v_lshlrev_b32_e32 v1, 2, v10
	v_add3_u32 v4, 16, v0, v1
	v_add_u32_e32 v6, 0x400, v4
	s_waitcnt lgkmcnt(0)
	s_barrier
	ds_read2_b32 v[0:1], v4 offset1:65
	ds_read2_b32 v[2:3], v4 offset0:130 offset1:195
	ds_read2_b32 v[4:5], v6 offset0:4 offset1:69
	ds_read2_b32 v[6:7], v6 offset0:134 offset1:199
	s_cmpk_gt_i32 s17, 0x7b0
	s_cbranch_scc1 .LBB0_82
	v_lshrrev_b32_e32 v11, 3, v8
	v_lshrrev_b32_e32 v12, 2, v8
	v_ashrrev_i32_e32 v8, 6, v8
	v_and_b32_e32 v12, 32, v12
	v_and_b32_e32 v8, -4, v8
	v_lshlrev_b32_e32 v10, 1, v10
	v_add_u32_e32 v8, v8, v12
	v_and_b32_e32 v10, 24, v10
	v_and_or_b32 v8, v11, 3, v8
	v_add_u32_e32 v10, v8, v10
	s_branch .LBB0_82

;     ...
; #pragma unroll
;     for (int r = 0; r < 2; ++r) {
;       const int e = tid + r * 512, i = e >> 4, j4 = (e & 15) * 4;
;       float4 v = make_float4(0.f, 0.f, 0.f, 0.f);
;       const int sn0 = upmap ? ((n0 & 255) >> 7) * DFF + (n0 >> 8) * 128 + (n0 & 127) : n0;
;       if (n0 + j4 < N) v = *reinterpret_cast<const float4*>(src + (size_t)(k0 + i) * N + sn0 + j4);
;       tile[i * 65 + j4] = v.x; tile[i * 65 + j4 + 1] = v.y; tile[i * 65 + j4 + 2] = v.z; tile[i * 65 + j4 + 3] = v.w;
;     }
;     __syncthreads();
.LBB0_98:
	s_or_b64 exec, exec, s[14:15]
	s_waitcnt vmcnt(1)
	ds_write2_b32 v10, v2, v3 offset1:1
	ds_write2_b32 v10, v4, v5 offset0:2 offset1:3
	v_mad_u64_u32 v[4:5], s[14:15], v24, s47, v[6:7]
	s_waitcnt vmcnt(0)
	ds_write2_b32 v4, v20, v21 offset1:1
	ds_write2_b32 v4, v22, v23 offset0:2 offset1:3
	v_lshlrev_b32_e32 v0, 3, v8
	v_ashrrev_i32_e32 v10, 3, v8
	v_and_b32_e32 v9, 56, v0
	v_mul_u32_u24_e32 v0, 0x104, v9
	v_lshlrev_b32_e32 v1, 2, v10
	v_add3_u32 v4, 16, v0, v1
	v_add_u32_e32 v6, 0x400, v4
	s_waitcnt lgkmcnt(0)
	s_barrier
	ds_read2_b32 v[0:1], v4 offset1:65
	ds_read2_b32 v[2:3], v4 offset0:130 offset1:195
	ds_read2_b32 v[4:5], v6 offset0:4 offset1:69
	ds_read2_b32 v[6:7], v6 offset0:134 offset1:199
	s_cmpk_gt_i32 s17, 0xd14
	s_cbranch_scc1 .LBB0_93
	v_lshrrev_b32_e32 v11, 3, v8
	v_lshrrev_b32_e32 v12, 2, v8
	v_ashrrev_i32_e32 v8, 6, v8
	v_and_b32_e32 v12, 32, v12
	v_and_b32_e32 v8, -4, v8
	v_lshlrev_b32_e32 v10, 1, v10
	v_add_u32_e32 v8, v8, v12
	v_and_b32_e32 v10, 24, v10
	v_and_or_b32 v8, v11, 3, v8
	v_add_u32_e32 v10, v8, v10
	s_branch .LBB0_93

;     ...
; #pragma unroll
;     for (int r = 0; r < 2; ++r) {
;       const int e = tid + r * 512, i = e >> 4, j4 = (e & 15) * 4;
;       float4 v = make_float4(0.f, 0.f, 0.f, 0.f);
;       const int sn0 = upmap ? ((n0 & 255) >> 7) * DFF + (n0 >> 8) * 128 + (n0 & 127) : n0;
;       if (n0 + j4 < N) v = *reinterpret_cast<const float4*>(src + (size_t)(k0 + i) * N + sn0 + j4);
;       tile[i * 65 + j4] = v.x; tile[i * 65 + j4 + 1] = v.y; tile[i * 65 + j4 + 2] = v.z; tile[i * 65 + j4 + 3] = v.w;
;     }
;     __syncthreads();
.LBB0_107:
	s_or_b64 exec, exec, s[14:15]
	v_lshl_add_u32 v6, v1, 2, 16
	v_mad_u64_u32 v[10:11], s[14:15], v7, s47, v[6:7]
	v_add_u32_e32 v1, 0x200, v8
	v_ashrrev_i32_e32 v24, 4, v1
	v_mov_b32_e32 v20, 0
	v_mov_b32_e32 v21, 0
	v_mov_b32_e32 v22, 0
	v_mov_b32_e32 v23, 0
	s_and_saveexec_b64 s[14:15], vcc
	s_cbranch_execz .LBB0_109
	v_add_u32_e32 v20, s8, v24
	v_ashrrev_i32_e32 v21, 31, v20
	v_lshlrev_b64 v[20:21], 10, v[20:21]
	v_lshl_add_u64 v[20:21], s[2:3], 0, v[20:21]
	s_ashr_i32 s13, s12, 31
	v_lshl_add_u64 v[20:21], s[12:13], 2, v[20:21]
	v_lshl_add_u64 v[20:21], v[20:21], 0, v[16:17]
	global_load_dwordx4 v[20:23], v[20:21], off
.LBB0_109:
	s_or_b64 exec, exec, s[14:15]
	s_waitcnt vmcnt(1)
	ds_write2_b32 v10, v2, v3 offset1:1
	ds_write2_b32 v10, v4, v5 offset0:2 offset1:3
	v_mad_u64_u32 v[4:5], s[14:15], v24, s47, v[6:7]
	s_waitcnt vmcnt(0)
	ds_write2_b32 v4, v20, v21 offset1:1
	ds_write2_b32 v4, v22, v23 offset0:2 offset1:3
	v_lshlrev_b32_e32 v0, 3, v8
	v_ashrrev_i32_e32 v10, 3, v8
	v_and_b32_e32 v9, 56, v0
	v_mul_u32_u24_e32 v0, 0x104, v9
	v_lshlrev_b32_e32 v1, 2, v10
	v_add3_u32 v4, 16, v0, v1
	v_add_u32_e32 v6, 0x400, v4
	s_waitcnt lgkmcnt(0)
	s_barrier
	ds_read2_b32 v[0:1], v4 offset1:65
	ds_read2_b32 v[2:3], v4 offset0:130 offset1:195
	ds_read2_b32 v[4:5], v6 offset0:4 offset1:69
	ds_read2_b32 v[6:7], v6 offset0:134 offset1:199
	s_cmpk_gt_i32 s17, 0xffc
	s_cbranch_scc1 .LBB0_104
	v_lshrrev_b32_e32 v11, 3, v8
	v_lshrrev_b32_e32 v12, 2, v8
	v_ashrrev_i32_e32 v8, 6, v8
	v_and_b32_e32 v12, 32, v12
	v_and_b32_e32 v8, -4, v8
	v_lshlrev_b32_e32 v10, 1, v10
	v_add_u32_e32 v8, v8, v12
	v_and_b32_e32 v10, 24, v10
	v_and_or_b32 v8, v11, 3, v8
	v_add_u32_e32 v10, v8, v10
	s_branch .LBB0_104

; DI f32v2 bfpair(unsigned q) { f32v2 r; r.x = __uint_as_float(q << 16); r.y = __uint_as_float(q & 0xffff0000u); return r; }
; DI void rwkv_scan_item(const PRef& p, int b, int h, int half) {
;     ...
;       for (int st = 0; st < 16; ++st) {
;         float4 wan, wbn, kan, kbn, ban, bbn; uint4 kqn, rqn; unsigned vqn;
;         if (st < 15) {
;           const char* sn = cb + (st + 1) * 1152;
;           wan = *reinterpret_cast<const float4*>(sn + ks * 4); wbn = *reinterpret_cast<const float4*>(sn + ks * 4 + 16);
;           kan = *reinterpret_cast<const float4*>(sn + 256 + ks * 4); kbn = *reinterpret_cast<const float4*>(sn + 256 + ks * 4 + 16);
;           ban = *reinterpret_cast<const float4*>(sn + 512 + ks * 4); bbn = *reinterpret_cast<const float4*>(sn + 512 + ks * 4 + 16);
;           kqn = *reinterpret_cast<const uint4*>(sn + 768 + ks * 2);
;           rqn = *reinterpret_cast<const uint4*>(sn + 896 + ks * 2);
;           vqn = *reinterpret_cast<const u16*>(sn + 1024 + row * 2);
;         }
;         const float v = __uint_as_float(vq << 16);
;         const f32v2 vv = {v, v};
;         const f32v2 kk01 = {ka.x, ka.y}, kk23 = {ka.z, ka.w}, kk45 = {kb.x, kb.y}, kk67 = {kb.z, kb.w};
;         f32v2 sa2 = S01 * kk01 + S23 * kk23;
;         f32v2 sb2 = S45 * kk45 + S67 * kk67;
;         sa2 += sb2;
;         float sa = row8_sum(sa2.x + sa2.y);
;         const f32v2 sav = {sa, sa};
;         S01 = S01 * f32v2{wa.x, wa.y} - sav * f32v2{ba.x, ba.y} + vv * bfpair(kq.x);
;         S23 = S23 * f32v2{wa.z, wa.w} - sav * f32v2{ba.z, ba.w} + vv * bfpair(kq.y);
;         S45 = S45 * f32v2{wb.x, wb.y} - sav * f32v2{bbv.x, bbv.y} + vv * bfpair(kq.z);
;         S67 = S67 * f32v2{wb.z, wb.w} - sav * f32v2{bbv.z, bbv.w} + vv * bfpair(kq.w);
;         f32v2 ya = S01 * bfpair(rq.x) + S23 * bfpair(rq.y);
;         f32v2 yb2 = S45 * bfpair(rq.z) + S67 * bfpair(rq.w);
;         ya += yb2;
;         float y = row8_sum(ya.x + ya.y);
;         yd[st * ystride] = y;
.Lrw_compute_h0:
	ds_read_b128 v[36:39], v101 offset:256
	ds_read_b128 v[72:75], v101 offset:1024
	ds_read_b128 v[48:51], v101 offset:768
	ds_read_u16_d16_hi v68, v97 offset:1280
	ds_read_b128 v[40:43], v101 offset:0
	ds_read_b128 v[44:47], v101 offset:512
	s_waitcnt lgkmcnt(0)
	v_pk_mul_f32 v[26:27], v[18:19], v[36:37]
	s_nop 0
	v_pk_fma_f32 v[26:27], v[20:21], v[38:39], v[26:27]
	s_nop 0
	v_add_f32_e32 v28, v26, v27
	ds_read_b128 v[52:55], v101 offset:1664
	ds_read_b128 v[76:79], v101 offset:2432
	v_add_f32_dpp v28, v28, v28 quad_perm:[1,0,3,2] row_mask:0xf bank_mask:0xf bound_ctrl:1
	ds_read_b128 v[64:67], v101 offset:2176
	ds_read_u16_d16_hi v70, v97 offset:2688
	v_add_f32_dpp v28, v28, v28 quad_perm:[2,3,0,1] row_mask:0xf bank_mask:0xf bound_ctrl:1
	ds_read_b128 v[56:59], v101 offset:1408
	ds_read_b128 v[60:63], v101 offset:1920
	v_add_f32_dpp v28, v28, v28 row_half_mirror row_mask:0xf bank_mask:0xf bound_ctrl:1
	v_pk_mul_f32 v[34:35], v[68:69], v[48:49] op_sel_hi:[0,1]
	v_pk_mul_f32 v[112:113], v[68:69], v[50:51] op_sel_hi:[0,1]
	v_add_f32_dpp v28, v28, v28 row_mirror row_mask:0xf bank_mask:0xf bound_ctrl:1
	v_pk_fma_f32 v[22:23], v[18:19], v[40:41], v[34:35]
	v_pk_fma_f32 v[24:25], v[20:21], v[42:43], v[112:113]
	v_pk_fma_f32 v[18:19], v[28:29], v[44:45], v[22:23] op_sel_hi:[0,1,1] neg_lo:[1,0,0] neg_hi:[1,0,0]
	v_pk_fma_f32 v[20:21], v[28:29], v[46:47], v[24:25] op_sel_hi:[0,1,1] neg_lo:[1,0,0] neg_hi:[1,0,0]
	s_waitcnt lgkmcnt(0)
	ds_read_b128 v[36:39], v101 offset:3072
	ds_read_b128 v[80:83], v101 offset:3840
	v_pk_mul_f32 v[26:27], v[18:19], v[52:53]
	v_pk_mul_f32 v[30:31], v[18:19], v[72:73]
	v_pk_fma_f32 v[26:27], v[20:21], v[54:55], v[26:27]
	v_pk_fma_f32 v[30:31], v[20:21], v[74:75], v[30:31]
	v_add_f32_e32 v28, v26, v27
	v_add_f32_e32 v32, v30, v31
	ds_read_b128 v[48:51], v101 offset:3584
	v_add_f32_dpp v28, v28, v28 quad_perm:[1,0,3,2] row_mask:0xf bank_mask:0xf bound_ctrl:1
	v_add_f32_dpp v32, v32, v32 quad_perm:[1,0,3,2] row_mask:0xf bank_mask:0xf bound_ctrl:1
	ds_read_u16_d16_hi v68, v97 offset:4096
	v_add_f32_dpp v28, v28, v28 quad_perm:[2,3,0,1] row_mask:0xf bank_mask:0xf bound_ctrl:1
	v_add_f32_dpp v32, v32, v32 quad_perm:[2,3,0,1] row_mask:0xf bank_mask:0xf bound_ctrl:1
	ds_read_b128 v[40:43], v101 offset:2816
	v_add_f32_dpp v28, v28, v28 row_half_mirror row_mask:0xf bank_mask:0xf bound_ctrl:1
	v_add_f32_dpp v32, v32, v32 row_half_mirror row_mask:0xf bank_mask:0xf bound_ctrl:1
	ds_read_b128 v[44:47], v101 offset:3328
	v_add_f32_dpp v28, v28, v28 row_mirror row_mask:0xf bank_mask:0xf bound_ctrl:1
	v_add_f32_dpp v32, v32, v32 row_mirror row_mask:0xf bank_mask:0xf bound_ctrl:1
	v_pk_mul_f32 v[34:35], v[70:71], v[64:65] op_sel_hi:[0,1]
	v_pk_mul_f32 v[112:113], v[70:71], v[66:67] op_sel_hi:[0,1]
	v_pk_fma_f32 v[22:23], v[18:19], v[56:57], v[34:35]
	v_pk_fma_f32 v[24:25], v[20:21], v[58:59], v[112:113]
	v_pk_fma_f32 v[18:19], v[28:29], v[60:61], v[22:23] op_sel_hi:[0,1,1] neg_lo:[1,0,0] neg_hi:[1,0,0]
	v_pk_fma_f32 v[20:21], v[28:29], v[62:63], v[24:25] op_sel_hi:[0,1,1] neg_lo:[1,0,0] neg_hi:[1,0,0]
	ds_write_b32 v108, v32 offset:0
	s_waitcnt lgkmcnt(1)
	ds_read_b128 v[52:55], v101 offset:4480
	ds_read_b128 v[72:75], v101 offset:5248
	v_pk_mul_f32 v[26:27], v[18:19], v[36:37]
	v_pk_mul_f32 v[30:31], v[18:19], v[76:77]
	v_pk_fma_f32 v[26:27], v[20:21], v[38:39], v[26:27]
	v_pk_fma_f32 v[30:31], v[20:21], v[78:79], v[30:31]
	v_add_f32_e32 v28, v26, v27
	v_add_f32_e32 v32, v30, v31
	ds_read_b128 v[64:67], v101 offset:4992
	v_add_f32_dpp v28, v28, v28 quad_perm:[1,0,3,2] row_mask:0xf bank_mask:0xf bound_ctrl:1
	v_add_f32_dpp v32, v32, v32 quad_perm:[1,0,3,2] row_mask:0xf bank_mask:0xf bound_ctrl:1
	ds_read_u16_d16_hi v70, v97 offset:5504
	v_add_f32_dpp v28, v28, v28 quad_perm:[2,3,0,1] row_mask:0xf bank_mask:0xf bound_ctrl:1
	v_add_f32_dpp v32, v32, v32 quad_perm:[2,3,0,1] row_mask:0xf bank_mask:0xf bound_ctrl:1
	ds_read_b128 v[56:59], v101 offset:4224
	v_add_f32_dpp v28, v28, v28 row_half_mirror row_mask:0xf bank_mask:0xf bound_ctrl:1
	v_add_f32_dpp v32, v32, v32 row_half_mirror row_mask:0xf bank_mask:0xf bound_ctrl:1
	ds_read_b128 v[60:63], v101 offset:4736
	v_add_f32_dpp v28, v28, v28 row_mirror row_mask:0xf bank_mask:0xf bound_ctrl:1
	v_add_f32_dpp v32, v32, v32 row_mirror row_mask:0xf bank_mask:0xf bound_ctrl:1
	v_pk_mul_f32 v[34:35], v[68:69], v[48:49] op_sel_hi:[0,1]
	v_pk_mul_f32 v[112:113], v[68:69], v[50:51] op_sel_hi:[0,1]
	v_pk_fma_f32 v[22:23], v[18:19], v[40:41], v[34:35]
	v_pk_fma_f32 v[24:25], v[20:21], v[42:43], v[112:113]
	v_pk_fma_f32 v[18:19], v[28:29], v[44:45], v[22:23] op_sel_hi:[0,1,1] neg_lo:[1,0,0] neg_hi:[1,0,0]
	v_pk_fma_f32 v[20:21], v[28:29], v[46:47], v[24:25] op_sel_hi:[0,1,1] neg_lo:[1,0,0] neg_hi:[1,0,0]
	ds_write_b32 v108, v32 offset:128
	s_waitcnt lgkmcnt(1)
	ds_read_b128 v[36:39], v101 offset:5888
	ds_read_b128 v[76:79], v101 offset:6656
	v_pk_mul_f32 v[26:27], v[18:19], v[52:53]
	v_pk_mul_f32 v[30:31], v[18:19], v[80:81]
	v_pk_fma_f32 v[26:27], v[20:21], v[54:55], v[26:27]
	v_pk_fma_f32 v[30:31], v[20:21], v[82:83], v[30:31]
	v_add_f32_e32 v28, v26, v27
	v_add_f32_e32 v32, v30, v31
	ds_read_b128 v[48:51], v101 offset:6400
	v_add_f32_dpp v28, v28, v28 quad_perm:[1,0,3,2] row_mask:0xf bank_mask:0xf bound_ctrl:1
	v_add_f32_dpp v32, v32, v32 quad_perm:[1,0,3,2] row_mask:0xf bank_mask:0xf bound_ctrl:1
	ds_read_u16_d16_hi v68, v97 offset:6912
	v_add_f32_dpp v28, v28, v28 quad_perm:[2,3,0,1] row_mask:0xf bank_mask:0xf bound_ctrl:1
	v_add_f32_dpp v32, v32, v32 quad_perm:[2,3,0,1] row_mask:0xf bank_mask:0xf bound_ctrl:1
	ds_read_b128 v[40:43], v101 offset:5632
	v_add_f32_dpp v28, v28, v28 row_half_mirror row_mask:0xf bank_mask:0xf bound_ctrl:1
	v_add_f32_dpp v32, v32, v32 row_half_mirror row_mask:0xf bank_mask:0xf bound_ctrl:1
	ds_read_b128 v[44:47], v101 offset:6144
	v_add_f32_dpp v28, v28, v28 row_mirror row_mask:0xf bank_mask:0xf bound_ctrl:1
	v_add_f32_dpp v32, v32, v32 row_mirror row_mask:0xf bank_mask:0xf bound_ctrl:1
	v_pk_mul_f32 v[34:35], v[70:71], v[64:65] op_sel_hi:[0,1]
	v_pk_mul_f32 v[112:113], v[70:71], v[66:67] op_sel_hi:[0,1]
	v_pk_fma_f32 v[22:23], v[18:19], v[56:57], v[34:35]
	v_pk_fma_f32 v[24:25], v[20:21], v[58:59], v[112:113]
	v_pk_fma_f32 v[18:19], v[28:29], v[60:61], v[22:23] op_sel_hi:[0,1,1] neg_lo:[1,0,0] neg_hi:[1,0,0]
	v_pk_fma_f32 v[20:21], v[28:29], v[62:63], v[24:25] op_sel_hi:[0,1,1] neg_lo:[1,0,0] neg_hi:[1,0,0]
	ds_write_b32 v108, v32 offset:256
	s_waitcnt lgkmcnt(1)
; DI f32v2 bfpair(unsigned q) { f32v2 r; r.x = __uint_as_float(q << 16); r.y = __uint_as_float(q & 0xffff0000u); return r; }
; DI void rwkv_scan_item(const PRef& p, int b, int h, int half) {
;     ...
;       for (int st = 0; st < 16; ++st) {
;         float4 wan, wbn, kan, kbn, ban, bbn; uint4 kqn, rqn; unsigned vqn;
;         if (st < 15) {
;           const char* sn = cb + (st + 1) * 1152;
;           wan = *reinterpret_cast<const float4*>(sn + ks * 4); wbn = *reinterpret_cast<const float4*>(sn + ks * 4 + 16);
;           kan = *reinterpret_cast<const float4*>(sn + 256 + ks * 4); kbn = *reinterpret_cast<const float4*>(sn + 256 + ks * 4 + 16);
;           ban = *reinterpret_cast<const float4*>(sn + 512 + ks * 4); bbn = *reinterpret_cast<const float4*>(sn + 512 + ks * 4 + 16);
;           kqn = *reinterpret_cast<const uint4*>(sn + 768 + ks * 2);
;           rqn = *reinterpret_cast<const uint4*>(sn + 896 + ks * 2);
;           vqn = *reinterpret_cast<const u16*>(sn + 1024 + row * 2);
;         }
;         const float v = __uint_as_float(vq << 16);
;         const f32v2 vv = {v, v};
;         const f32v2 kk01 = {ka.x, ka.y}, kk23 = {ka.z, ka.w}, kk45 = {kb.x, kb.y}, kk67 = {kb.z, kb.w};
;         f32v2 sa2 = S01 * kk01 + S23 * kk23;
;         f32v2 sb2 = S45 * kk45 + S67 * kk67;
;         sa2 += sb2;
;         float sa = row8_sum(sa2.x + sa2.y);
;         const f32v2 sav = {sa, sa};
;         S01 = S01 * f32v2{wa.x, wa.y} - sav * f32v2{ba.x, ba.y} + vv * bfpair(kq.x);
;         S23 = S23 * f32v2{wa.z, wa.w} - sav * f32v2{ba.z, ba.w} + vv * bfpair(kq.y);
;         S45 = S45 * f32v2{wb.x, wb.y} - sav * f32v2{bbv.x, bbv.y} + vv * bfpair(kq.z);
;         S67 = S67 * f32v2{wb.z, wb.w} - sav * f32v2{bbv.z, bbv.w} + vv * bfpair(kq.w);
;         f32v2 ya = S01 * bfpair(rq.x) + S23 * bfpair(rq.y);
;         f32v2 yb2 = S45 * bfpair(rq.z) + S67 * bfpair(rq.w);
;         ya += yb2;
;         float y = row8_sum(ya.x + ya.y);
;         yd[st * ystride] = y;
	ds_read_b128 v[52:55], v101 offset:7296
	ds_read_b128 v[80:83], v101 offset:8064
	v_pk_mul_f32 v[26:27], v[18:19], v[36:37]
	v_pk_mul_f32 v[30:31], v[18:19], v[72:73]
	v_pk_fma_f32 v[26:27], v[20:21], v[38:39], v[26:27]
	v_pk_fma_f32 v[30:31], v[20:21], v[74:75], v[30:31]
	v_add_f32_e32 v28, v26, v27
	v_add_f32_e32 v32, v30, v31
	ds_read_b128 v[64:67], v101 offset:7808
	v_add_f32_dpp v28, v28, v28 quad_perm:[1,0,3,2] row_mask:0xf bank_mask:0xf bound_ctrl:1
	v_add_f32_dpp v32, v32, v32 quad_perm:[1,0,3,2] row_mask:0xf bank_mask:0xf bound_ctrl:1
	ds_read_u16_d16_hi v70, v97 offset:8320
	v_add_f32_dpp v28, v28, v28 quad_perm:[2,3,0,1] row_mask:0xf bank_mask:0xf bound_ctrl:1
	v_add_f32_dpp v32, v32, v32 quad_perm:[2,3,0,1] row_mask:0xf bank_mask:0xf bound_ctrl:1
	ds_read_b128 v[56:59], v101 offset:7040
	v_add_f32_dpp v28, v28, v28 row_half_mirror row_mask:0xf bank_mask:0xf bound_ctrl:1
	v_add_f32_dpp v32, v32, v32 row_half_mirror row_mask:0xf bank_mask:0xf bound_ctrl:1
	ds_read_b128 v[60:63], v101 offset:7552
	v_add_f32_dpp v28, v28, v28 row_mirror row_mask:0xf bank_mask:0xf bound_ctrl:1
	v_add_f32_dpp v32, v32, v32 row_mirror row_mask:0xf bank_mask:0xf bound_ctrl:1
	v_pk_mul_f32 v[34:35], v[68:69], v[48:49] op_sel_hi:[0,1]
	v_pk_mul_f32 v[112:113], v[68:69], v[50:51] op_sel_hi:[0,1]
	v_pk_fma_f32 v[22:23], v[18:19], v[40:41], v[34:35]
	v_pk_fma_f32 v[24:25], v[20:21], v[42:43], v[112:113]
	v_pk_fma_f32 v[18:19], v[28:29], v[44:45], v[22:23] op_sel_hi:[0,1,1] neg_lo:[1,0,0] neg_hi:[1,0,0]
	v_pk_fma_f32 v[20:21], v[28:29], v[46:47], v[24:25] op_sel_hi:[0,1,1] neg_lo:[1,0,0] neg_hi:[1,0,0]
	ds_write_b32 v108, v32 offset:384
	s_waitcnt lgkmcnt(1)
	ds_read_b128 v[36:39], v101 offset:8704
	ds_read_b128 v[72:75], v101 offset:9472
	v_pk_mul_f32 v[26:27], v[18:19], v[52:53]
	v_pk_mul_f32 v[30:31], v[18:19], v[76:77]
	v_pk_fma_f32 v[26:27], v[20:21], v[54:55], v[26:27]
	v_pk_fma_f32 v[30:31], v[20:21], v[78:79], v[30:31]
	v_add_f32_e32 v28, v26, v27
	v_add_f32_e32 v32, v30, v31
	ds_read_b128 v[48:51], v101 offset:9216
	v_add_f32_dpp v28, v28, v28 quad_perm:[1,0,3,2] row_mask:0xf bank_mask:0xf bound_ctrl:1
	v_add_f32_dpp v32, v32, v32 quad_perm:[1,0,3,2] row_mask:0xf bank_mask:0xf bound_ctrl:1
	ds_read_u16_d16_hi v68, v97 offset:9728
	v_add_f32_dpp v28, v28, v28 quad_perm:[2,3,0,1] row_mask:0xf bank_mask:0xf bound_ctrl:1
	v_add_f32_dpp v32, v32, v32 quad_perm:[2,3,0,1] row_mask:0xf bank_mask:0xf bound_ctrl:1
	ds_read_b128 v[40:43], v101 offset:8448
	v_add_f32_dpp v28, v28, v28 row_half_mirror row_mask:0xf bank_mask:0xf bound_ctrl:1
	v_add_f32_dpp v32, v32, v32 row_half_mirror row_mask:0xf bank_mask:0xf bound_ctrl:1
	ds_read_b128 v[44:47], v101 offset:8960
	v_add_f32_dpp v28, v28, v28 row_mirror row_mask:0xf bank_mask:0xf bound_ctrl:1
	v_add_f32_dpp v32, v32, v32 row_mirror row_mask:0xf bank_mask:0xf bound_ctrl:1
	v_pk_mul_f32 v[34:35], v[70:71], v[64:65] op_sel_hi:[0,1]
	v_pk_mul_f32 v[112:113], v[70:71], v[66:67] op_sel_hi:[0,1]
	v_pk_fma_f32 v[22:23], v[18:19], v[56:57], v[34:35]
	v_pk_fma_f32 v[24:25], v[20:21], v[58:59], v[112:113]
	v_pk_fma_f32 v[18:19], v[28:29], v[60:61], v[22:23] op_sel_hi:[0,1,1] neg_lo:[1,0,0] neg_hi:[1,0,0]
	v_pk_fma_f32 v[20:21], v[28:29], v[62:63], v[24:25] op_sel_hi:[0,1,1] neg_lo:[1,0,0] neg_hi:[1,0,0]
	ds_write_b32 v108, v32 offset:512
	s_waitcnt lgkmcnt(1)
	ds_read_b128 v[52:55], v101 offset:10112
	ds_read_b128 v[76:79], v101 offset:10880
	v_pk_mul_f32 v[26:27], v[18:19], v[36:37]
	v_pk_mul_f32 v[30:31], v[18:19], v[80:81]
	v_pk_fma_f32 v[26:27], v[20:21], v[38:39], v[26:27]
	v_pk_fma_f32 v[30:31], v[20:21], v[82:83], v[30:31]
	v_add_f32_e32 v28, v26, v27
	v_add_f32_e32 v32, v30, v31
	ds_read_b128 v[64:67], v101 offset:10624
	v_add_f32_dpp v28, v28, v28 quad_perm:[1,0,3,2] row_mask:0xf bank_mask:0xf bound_ctrl:1
	v_add_f32_dpp v32, v32, v32 quad_perm:[1,0,3,2] row_mask:0xf bank_mask:0xf bound_ctrl:1
	ds_read_u16_d16_hi v70, v97 offset:11136
	v_add_f32_dpp v28, v28, v28 quad_perm:[2,3,0,1] row_mask:0xf bank_mask:0xf bound_ctrl:1
	v_add_f32_dpp v32, v32, v32 quad_perm:[2,3,0,1] row_mask:0xf bank_mask:0xf bound_ctrl:1
	ds_read_b128 v[56:59], v101 offset:9856
	v_add_f32_dpp v28, v28, v28 row_half_mirror row_mask:0xf bank_mask:0xf bound_ctrl:1
	v_add_f32_dpp v32, v32, v32 row_half_mirror row_mask:0xf bank_mask:0xf bound_ctrl:1
	ds_read_b128 v[60:63], v101 offset:10368
	v_add_f32_dpp v28, v28, v28 row_mirror row_mask:0xf bank_mask:0xf bound_ctrl:1
	v_add_f32_dpp v32, v32, v32 row_mirror row_mask:0xf bank_mask:0xf bound_ctrl:1
	v_pk_mul_f32 v[34:35], v[68:69], v[48:49] op_sel_hi:[0,1]
	v_pk_mul_f32 v[112:113], v[68:69], v[50:51] op_sel_hi:[0,1]
	v_pk_fma_f32 v[22:23], v[18:19], v[40:41], v[34:35]
	v_pk_fma_f32 v[24:25], v[20:21], v[42:43], v[112:113]
	v_pk_fma_f32 v[18:19], v[28:29], v[44:45], v[22:23] op_sel_hi:[0,1,1] neg_lo:[1,0,0] neg_hi:[1,0,0]
	v_pk_fma_f32 v[20:21], v[28:29], v[46:47], v[24:25] op_sel_hi:[0,1,1] neg_lo:[1,0,0] neg_hi:[1,0,0]
	ds_write_b32 v108, v32 offset:640
	s_waitcnt lgkmcnt(1)
; DI f32v2 bfpair(unsigned q) { f32v2 r; r.x = __uint_as_float(q << 16); r.y = __uint_as_float(q & 0xffff0000u); return r; }
; DI void rwkv_scan_item(const PRef& p, int b, int h, int half) {
;     ...
;       for (int st = 0; st < 16; ++st) {
;         float4 wan, wbn, kan, kbn, ban, bbn; uint4 kqn, rqn; unsigned vqn;
;         if (st < 15) {
;           const char* sn = cb + (st + 1) * 1152;
;           wan = *reinterpret_cast<const float4*>(sn + ks * 4); wbn = *reinterpret_cast<const float4*>(sn + ks * 4 + 16);
;           kan = *reinterpret_cast<const float4*>(sn + 256 + ks * 4); kbn = *reinterpret_cast<const float4*>(sn + 256 + ks * 4 + 16);
;           ban = *reinterpret_cast<const float4*>(sn + 512 + ks * 4); bbn = *reinterpret_cast<const float4*>(sn + 512 + ks * 4 + 16);
;           kqn = *reinterpret_cast<const uint4*>(sn + 768 + ks * 2);
;           rqn = *reinterpret_cast<const uint4*>(sn + 896 + ks * 2);
;           vqn = *reinterpret_cast<const u16*>(sn + 1024 + row * 2);
;         }
;         const float v = __uint_as_float(vq << 16);
;         const f32v2 vv = {v, v};
;         const f32v2 kk01 = {ka.x, ka.y}, kk23 = {ka.z, ka.w}, kk45 = {kb.x, kb.y}, kk67 = {kb.z, kb.w};
;         f32v2 sa2 = S01 * kk01 + S23 * kk23;
;         f32v2 sb2 = S45 * kk45 + S67 * kk67;
;         sa2 += sb2;
;         float sa = row8_sum(sa2.x + sa2.y);
;         const f32v2 sav = {sa, sa};
;         S01 = S01 * f32v2{wa.x, wa.y} - sav * f32v2{ba.x, ba.y} + vv * bfpair(kq.x);
;         S23 = S23 * f32v2{wa.z, wa.w} - sav * f32v2{ba.z, ba.w} + vv * bfpair(kq.y);
;         S45 = S45 * f32v2{wb.x, wb.y} - sav * f32v2{bbv.x, bbv.y} + vv * bfpair(kq.z);
;         S67 = S67 * f32v2{wb.z, wb.w} - sav * f32v2{bbv.z, bbv.w} + vv * bfpair(kq.w);
;         f32v2 ya = S01 * bfpair(rq.x) + S23 * bfpair(rq.y);
;         f32v2 yb2 = S45 * bfpair(rq.z) + S67 * bfpair(rq.w);
;         ya += yb2;
;         float y = row8_sum(ya.x + ya.y);
;         yd[st * ystride] = y;
	ds_read_b128 v[36:39], v101 offset:11520
	ds_read_b128 v[80:83], v101 offset:12288
	v_pk_mul_f32 v[26:27], v[18:19], v[52:53]
	v_pk_mul_f32 v[30:31], v[18:19], v[72:73]
	v_pk_fma_f32 v[26:27], v[20:21], v[54:55], v[26:27]
	v_pk_fma_f32 v[30:31], v[20:21], v[74:75], v[30:31]
	v_add_f32_e32 v28, v26, v27
	v_add_f32_e32 v32, v30, v31
	ds_read_b128 v[48:51], v101 offset:12032
	v_add_f32_dpp v28, v28, v28 quad_perm:[1,0,3,2] row_mask:0xf bank_mask:0xf bound_ctrl:1
	v_add_f32_dpp v32, v32, v32 quad_perm:[1,0,3,2] row_mask:0xf bank_mask:0xf bound_ctrl:1
	ds_read_u16_d16_hi v68, v97 offset:12544
	v_add_f32_dpp v28, v28, v28 quad_perm:[2,3,0,1] row_mask:0xf bank_mask:0xf bound_ctrl:1
	v_add_f32_dpp v32, v32, v32 quad_perm:[2,3,0,1] row_mask:0xf bank_mask:0xf bound_ctrl:1
	ds_read_b128 v[40:43], v101 offset:11264
	v_add_f32_dpp v28, v28, v28 row_half_mirror row_mask:0xf bank_mask:0xf bound_ctrl:1
	v_add_f32_dpp v32, v32, v32 row_half_mirror row_mask:0xf bank_mask:0xf bound_ctrl:1
	ds_read_b128 v[44:47], v101 offset:11776
	v_add_f32_dpp v28, v28, v28 row_mirror row_mask:0xf bank_mask:0xf bound_ctrl:1
	v_add_f32_dpp v32, v32, v32 row_mirror row_mask:0xf bank_mask:0xf bound_ctrl:1
	v_pk_mul_f32 v[34:35], v[70:71], v[64:65] op_sel_hi:[0,1]
	v_pk_mul_f32 v[112:113], v[70:71], v[66:67] op_sel_hi:[0,1]
	v_pk_fma_f32 v[22:23], v[18:19], v[56:57], v[34:35]
	v_pk_fma_f32 v[24:25], v[20:21], v[58:59], v[112:113]
	v_pk_fma_f32 v[18:19], v[28:29], v[60:61], v[22:23] op_sel_hi:[0,1,1] neg_lo:[1,0,0] neg_hi:[1,0,0]
	v_pk_fma_f32 v[20:21], v[28:29], v[62:63], v[24:25] op_sel_hi:[0,1,1] neg_lo:[1,0,0] neg_hi:[1,0,0]
	ds_write_b32 v108, v32 offset:768
	s_waitcnt lgkmcnt(1)
	ds_read_b128 v[52:55], v101 offset:12928
	ds_read_b128 v[72:75], v101 offset:13696
	v_pk_mul_f32 v[26:27], v[18:19], v[36:37]
	v_pk_mul_f32 v[30:31], v[18:19], v[76:77]
	v_pk_fma_f32 v[26:27], v[20:21], v[38:39], v[26:27]
	v_pk_fma_f32 v[30:31], v[20:21], v[78:79], v[30:31]
	v_add_f32_e32 v28, v26, v27
	v_add_f32_e32 v32, v30, v31
	ds_read_b128 v[64:67], v101 offset:13440
	v_add_f32_dpp v28, v28, v28 quad_perm:[1,0,3,2] row_mask:0xf bank_mask:0xf bound_ctrl:1
	v_add_f32_dpp v32, v32, v32 quad_perm:[1,0,3,2] row_mask:0xf bank_mask:0xf bound_ctrl:1
	ds_read_u16_d16_hi v70, v97 offset:13952
	v_add_f32_dpp v28, v28, v28 quad_perm:[2,3,0,1] row_mask:0xf bank_mask:0xf bound_ctrl:1
	v_add_f32_dpp v32, v32, v32 quad_perm:[2,3,0,1] row_mask:0xf bank_mask:0xf bound_ctrl:1
	ds_read_b128 v[56:59], v101 offset:12672
	v_add_f32_dpp v28, v28, v28 row_half_mirror row_mask:0xf bank_mask:0xf bound_ctrl:1
	v_add_f32_dpp v32, v32, v32 row_half_mirror row_mask:0xf bank_mask:0xf bound_ctrl:1
	ds_read_b128 v[60:63], v101 offset:13184
	v_add_f32_dpp v28, v28, v28 row_mirror row_mask:0xf bank_mask:0xf bound_ctrl:1
	v_add_f32_dpp v32, v32, v32 row_mirror row_mask:0xf bank_mask:0xf bound_ctrl:1
	v_pk_mul_f32 v[34:35], v[68:69], v[48:49] op_sel_hi:[0,1]
	v_pk_mul_f32 v[112:113], v[68:69], v[50:51] op_sel_hi:[0,1]
	v_pk_fma_f32 v[22:23], v[18:19], v[40:41], v[34:35]
	v_pk_fma_f32 v[24:25], v[20:21], v[42:43], v[112:113]
	v_pk_fma_f32 v[18:19], v[28:29], v[44:45], v[22:23] op_sel_hi:[0,1,1] neg_lo:[1,0,0] neg_hi:[1,0,0]
	v_pk_fma_f32 v[20:21], v[28:29], v[46:47], v[24:25] op_sel_hi:[0,1,1] neg_lo:[1,0,0] neg_hi:[1,0,0]
	ds_write_b32 v108, v32 offset:896
	s_waitcnt lgkmcnt(1)
	ds_read_b128 v[36:39], v101 offset:14336
	ds_read_b128 v[76:79], v101 offset:15104
	v_pk_mul_f32 v[26:27], v[18:19], v[52:53]
	v_pk_mul_f32 v[30:31], v[18:19], v[80:81]
	v_pk_fma_f32 v[26:27], v[20:21], v[54:55], v[26:27]
	v_pk_fma_f32 v[30:31], v[20:21], v[82:83], v[30:31]
	v_add_f32_e32 v28, v26, v27
	v_add_f32_e32 v32, v30, v31
	ds_read_b128 v[48:51], v101 offset:14848
	v_add_f32_dpp v28, v28, v28 quad_perm:[1,0,3,2] row_mask:0xf bank_mask:0xf bound_ctrl:1
	v_add_f32_dpp v32, v32, v32 quad_perm:[1,0,3,2] row_mask:0xf bank_mask:0xf bound_ctrl:1
	ds_read_u16_d16_hi v68, v97 offset:15360
	v_add_f32_dpp v28, v28, v28 quad_perm:[2,3,0,1] row_mask:0xf bank_mask:0xf bound_ctrl:1
	v_add_f32_dpp v32, v32, v32 quad_perm:[2,3,0,1] row_mask:0xf bank_mask:0xf bound_ctrl:1
	ds_read_b128 v[40:43], v101 offset:14080
	v_add_f32_dpp v28, v28, v28 row_half_mirror row_mask:0xf bank_mask:0xf bound_ctrl:1
	v_add_f32_dpp v32, v32, v32 row_half_mirror row_mask:0xf bank_mask:0xf bound_ctrl:1
	ds_read_b128 v[44:47], v101 offset:14592
	v_add_f32_dpp v28, v28, v28 row_mirror row_mask:0xf bank_mask:0xf bound_ctrl:1
	v_add_f32_dpp v32, v32, v32 row_mirror row_mask:0xf bank_mask:0xf bound_ctrl:1
	v_pk_mul_f32 v[34:35], v[70:71], v[64:65] op_sel_hi:[0,1]
	v_pk_mul_f32 v[112:113], v[70:71], v[66:67] op_sel_hi:[0,1]
	v_pk_fma_f32 v[22:23], v[18:19], v[56:57], v[34:35]
	v_pk_fma_f32 v[24:25], v[20:21], v[58:59], v[112:113]
	v_pk_fma_f32 v[18:19], v[28:29], v[60:61], v[22:23] op_sel_hi:[0,1,1] neg_lo:[1,0,0] neg_hi:[1,0,0]
	v_pk_fma_f32 v[20:21], v[28:29], v[62:63], v[24:25] op_sel_hi:[0,1,1] neg_lo:[1,0,0] neg_hi:[1,0,0]
	ds_write_b32 v108, v32 offset:1024
	s_waitcnt lgkmcnt(1)
; DI f32v2 bfpair(unsigned q) { f32v2 r; r.x = __uint_as_float(q << 16); r.y = __uint_as_float(q & 0xffff0000u); return r; }
; DI void rwkv_scan_item(const PRef& p, int b, int h, int half) {
;     ...
;       for (int st = 0; st < 16; ++st) {
;         float4 wan, wbn, kan, kbn, ban, bbn; uint4 kqn, rqn; unsigned vqn;
;         if (st < 15) {
;           const char* sn = cb + (st + 1) * 1152;
;           wan = *reinterpret_cast<const float4*>(sn + ks * 4); wbn = *reinterpret_cast<const float4*>(sn + ks * 4 + 16);
;           kan = *reinterpret_cast<const float4*>(sn + 256 + ks * 4); kbn = *reinterpret_cast<const float4*>(sn + 256 + ks * 4 + 16);
;           ban = *reinterpret_cast<const float4*>(sn + 512 + ks * 4); bbn = *reinterpret_cast<const float4*>(sn + 512 + ks * 4 + 16);
;           kqn = *reinterpret_cast<const uint4*>(sn + 768 + ks * 2);
;           rqn = *reinterpret_cast<const uint4*>(sn + 896 + ks * 2);
;           vqn = *reinterpret_cast<const u16*>(sn + 1024 + row * 2);
;         }
;         const float v = __uint_as_float(vq << 16);
;         const f32v2 vv = {v, v};
;         const f32v2 kk01 = {ka.x, ka.y}, kk23 = {ka.z, ka.w}, kk45 = {kb.x, kb.y}, kk67 = {kb.z, kb.w};
;         f32v2 sa2 = S01 * kk01 + S23 * kk23;
;         f32v2 sb2 = S45 * kk45 + S67 * kk67;
;         sa2 += sb2;
;         float sa = row8_sum(sa2.x + sa2.y);
;         const f32v2 sav = {sa, sa};
;         S01 = S01 * f32v2{wa.x, wa.y} - sav * f32v2{ba.x, ba.y} + vv * bfpair(kq.x);
;         S23 = S23 * f32v2{wa.z, wa.w} - sav * f32v2{ba.z, ba.w} + vv * bfpair(kq.y);
;         S45 = S45 * f32v2{wb.x, wb.y} - sav * f32v2{bbv.x, bbv.y} + vv * bfpair(kq.z);
;         S67 = S67 * f32v2{wb.z, wb.w} - sav * f32v2{bbv.z, bbv.w} + vv * bfpair(kq.w);
;         f32v2 ya = S01 * bfpair(rq.x) + S23 * bfpair(rq.y);
;         f32v2 yb2 = S45 * bfpair(rq.z) + S67 * bfpair(rq.w);
;         ya += yb2;
;         float y = row8_sum(ya.x + ya.y);
;         yd[st * ystride] = y;
	ds_read_b128 v[52:55], v101 offset:15744
	ds_read_b128 v[80:83], v101 offset:16512
	v_pk_mul_f32 v[26:27], v[18:19], v[36:37]
	v_pk_mul_f32 v[30:31], v[18:19], v[72:73]
	v_pk_fma_f32 v[26:27], v[20:21], v[38:39], v[26:27]
	v_pk_fma_f32 v[30:31], v[20:21], v[74:75], v[30:31]
	v_add_f32_e32 v28, v26, v27
	v_add_f32_e32 v32, v30, v31
	ds_read_b128 v[64:67], v101 offset:16256
	v_add_f32_dpp v28, v28, v28 quad_perm:[1,0,3,2] row_mask:0xf bank_mask:0xf bound_ctrl:1
	v_add_f32_dpp v32, v32, v32 quad_perm:[1,0,3,2] row_mask:0xf bank_mask:0xf bound_ctrl:1
	ds_read_u16_d16_hi v70, v97 offset:16768
	v_add_f32_dpp v28, v28, v28 quad_perm:[2,3,0,1] row_mask:0xf bank_mask:0xf bound_ctrl:1
	v_add_f32_dpp v32, v32, v32 quad_perm:[2,3,0,1] row_mask:0xf bank_mask:0xf bound_ctrl:1
	ds_read_b128 v[56:59], v101 offset:15488
	v_add_f32_dpp v28, v28, v28 row_half_mirror row_mask:0xf bank_mask:0xf bound_ctrl:1
	v_add_f32_dpp v32, v32, v32 row_half_mirror row_mask:0xf bank_mask:0xf bound_ctrl:1
	ds_read_b128 v[60:63], v101 offset:16000
	v_add_f32_dpp v28, v28, v28 row_mirror row_mask:0xf bank_mask:0xf bound_ctrl:1
	v_add_f32_dpp v32, v32, v32 row_mirror row_mask:0xf bank_mask:0xf bound_ctrl:1
	v_pk_mul_f32 v[34:35], v[68:69], v[48:49] op_sel_hi:[0,1]
	v_pk_mul_f32 v[112:113], v[68:69], v[50:51] op_sel_hi:[0,1]
	v_pk_fma_f32 v[22:23], v[18:19], v[40:41], v[34:35]
	v_pk_fma_f32 v[24:25], v[20:21], v[42:43], v[112:113]
	v_pk_fma_f32 v[18:19], v[28:29], v[44:45], v[22:23] op_sel_hi:[0,1,1] neg_lo:[1,0,0] neg_hi:[1,0,0]
	v_pk_fma_f32 v[20:21], v[28:29], v[46:47], v[24:25] op_sel_hi:[0,1,1] neg_lo:[1,0,0] neg_hi:[1,0,0]
	ds_write_b32 v108, v32 offset:1152
	s_waitcnt lgkmcnt(1)
	ds_read_b128 v[36:39], v101 offset:17152
	ds_read_b128 v[72:75], v101 offset:17920
	v_pk_mul_f32 v[26:27], v[18:19], v[52:53]
	v_pk_mul_f32 v[30:31], v[18:19], v[76:77]
	v_pk_fma_f32 v[26:27], v[20:21], v[54:55], v[26:27]
	v_pk_fma_f32 v[30:31], v[20:21], v[78:79], v[30:31]
	v_add_f32_e32 v28, v26, v27
	v_add_f32_e32 v32, v30, v31
	ds_read_b128 v[48:51], v101 offset:17664
	v_add_f32_dpp v28, v28, v28 quad_perm:[1,0,3,2] row_mask:0xf bank_mask:0xf bound_ctrl:1
	v_add_f32_dpp v32, v32, v32 quad_perm:[1,0,3,2] row_mask:0xf bank_mask:0xf bound_ctrl:1
	ds_read_u16_d16_hi v68, v97 offset:18176
	v_add_f32_dpp v28, v28, v28 quad_perm:[2,3,0,1] row_mask:0xf bank_mask:0xf bound_ctrl:1
	v_add_f32_dpp v32, v32, v32 quad_perm:[2,3,0,1] row_mask:0xf bank_mask:0xf bound_ctrl:1
	ds_read_b128 v[40:43], v101 offset:16896
	v_add_f32_dpp v28, v28, v28 row_half_mirror row_mask:0xf bank_mask:0xf bound_ctrl:1
	v_add_f32_dpp v32, v32, v32 row_half_mirror row_mask:0xf bank_mask:0xf bound_ctrl:1
	ds_read_b128 v[44:47], v101 offset:17408
	v_add_f32_dpp v28, v28, v28 row_mirror row_mask:0xf bank_mask:0xf bound_ctrl:1
	v_add_f32_dpp v32, v32, v32 row_mirror row_mask:0xf bank_mask:0xf bound_ctrl:1
	v_pk_mul_f32 v[34:35], v[70:71], v[64:65] op_sel_hi:[0,1]
	v_pk_mul_f32 v[112:113], v[70:71], v[66:67] op_sel_hi:[0,1]
	v_pk_fma_f32 v[22:23], v[18:19], v[56:57], v[34:35]
	v_pk_fma_f32 v[24:25], v[20:21], v[58:59], v[112:113]
	v_pk_fma_f32 v[18:19], v[28:29], v[60:61], v[22:23] op_sel_hi:[0,1,1] neg_lo:[1,0,0] neg_hi:[1,0,0]
	v_pk_fma_f32 v[20:21], v[28:29], v[62:63], v[24:25] op_sel_hi:[0,1,1] neg_lo:[1,0,0] neg_hi:[1,0,0]
	ds_write_b32 v108, v32 offset:1280
	s_waitcnt lgkmcnt(1)
	ds_read_b128 v[52:55], v101 offset:18560
	ds_read_b128 v[76:79], v101 offset:19328
	v_pk_mul_f32 v[26:27], v[18:19], v[36:37]
	v_pk_mul_f32 v[30:31], v[18:19], v[80:81]
	v_pk_fma_f32 v[26:27], v[20:21], v[38:39], v[26:27]
	v_pk_fma_f32 v[30:31], v[20:21], v[82:83], v[30:31]
	v_add_f32_e32 v28, v26, v27
	v_add_f32_e32 v32, v30, v31
	ds_read_b128 v[64:67], v101 offset:19072
	v_add_f32_dpp v28, v28, v28 quad_perm:[1,0,3,2] row_mask:0xf bank_mask:0xf bound_ctrl:1
	v_add_f32_dpp v32, v32, v32 quad_perm:[1,0,3,2] row_mask:0xf bank_mask:0xf bound_ctrl:1
	ds_read_u16_d16_hi v70, v97 offset:19584
	v_add_f32_dpp v28, v28, v28 quad_perm:[2,3,0,1] row_mask:0xf bank_mask:0xf bound_ctrl:1
	v_add_f32_dpp v32, v32, v32 quad_perm:[2,3,0,1] row_mask:0xf bank_mask:0xf bound_ctrl:1
	ds_read_b128 v[56:59], v101 offset:18304
	v_add_f32_dpp v28, v28, v28 row_half_mirror row_mask:0xf bank_mask:0xf bound_ctrl:1
	v_add_f32_dpp v32, v32, v32 row_half_mirror row_mask:0xf bank_mask:0xf bound_ctrl:1
	ds_read_b128 v[60:63], v101 offset:18816
	v_add_f32_dpp v28, v28, v28 row_mirror row_mask:0xf bank_mask:0xf bound_ctrl:1
	v_add_f32_dpp v32, v32, v32 row_mirror row_mask:0xf bank_mask:0xf bound_ctrl:1
	v_pk_mul_f32 v[34:35], v[68:69], v[48:49] op_sel_hi:[0,1]
	v_pk_mul_f32 v[112:113], v[68:69], v[50:51] op_sel_hi:[0,1]
	v_pk_fma_f32 v[22:23], v[18:19], v[40:41], v[34:35]
	v_pk_fma_f32 v[24:25], v[20:21], v[42:43], v[112:113]
	v_pk_fma_f32 v[18:19], v[28:29], v[44:45], v[22:23] op_sel_hi:[0,1,1] neg_lo:[1,0,0] neg_hi:[1,0,0]
	v_pk_fma_f32 v[20:21], v[28:29], v[46:47], v[24:25] op_sel_hi:[0,1,1] neg_lo:[1,0,0] neg_hi:[1,0,0]
	ds_write_b32 v108, v32 offset:1408
	s_waitcnt lgkmcnt(1)
; DI f32v2 bfpair(unsigned q) { f32v2 r; r.x = __uint_as_float(q << 16); r.y = __uint_as_float(q & 0xffff0000u); return r; }
; DI void rwkv_scan_item(const PRef& p, int b, int h, int half) {
;     ...
;       for (int st = 0; st < 16; ++st) {
;         float4 wan, wbn, kan, kbn, ban, bbn; uint4 kqn, rqn; unsigned vqn;
;         if (st < 15) {
;           const char* sn = cb + (st + 1) * 1152;
;           wan = *reinterpret_cast<const float4*>(sn + ks * 4); wbn = *reinterpret_cast<const float4*>(sn + ks * 4 + 16);
;           kan = *reinterpret_cast<const float4*>(sn + 256 + ks * 4); kbn = *reinterpret_cast<const float4*>(sn + 256 + ks * 4 + 16);
;           ban = *reinterpret_cast<const float4*>(sn + 512 + ks * 4); bbn = *reinterpret_cast<const float4*>(sn + 512 + ks * 4 + 16);
;           kqn = *reinterpret_cast<const uint4*>(sn + 768 + ks * 2);
;           rqn = *reinterpret_cast<const uint4*>(sn + 896 + ks * 2);
;           vqn = *reinterpret_cast<const u16*>(sn + 1024 + row * 2);
;         }
;         const float v = __uint_as_float(vq << 16);
;         const f32v2 vv = {v, v};
;         const f32v2 kk01 = {ka.x, ka.y}, kk23 = {ka.z, ka.w}, kk45 = {kb.x, kb.y}, kk67 = {kb.z, kb.w};
;         f32v2 sa2 = S01 * kk01 + S23 * kk23;
;         f32v2 sb2 = S45 * kk45 + S67 * kk67;
;         sa2 += sb2;
;         float sa = row8_sum(sa2.x + sa2.y);
;         const f32v2 sav = {sa, sa};
;         S01 = S01 * f32v2{wa.x, wa.y} - sav * f32v2{ba.x, ba.y} + vv * bfpair(kq.x);
;         S23 = S23 * f32v2{wa.z, wa.w} - sav * f32v2{ba.z, ba.w} + vv * bfpair(kq.y);
;         S45 = S45 * f32v2{wb.x, wb.y} - sav * f32v2{bbv.x, bbv.y} + vv * bfpair(kq.z);
;         S67 = S67 * f32v2{wb.z, wb.w} - sav * f32v2{bbv.z, bbv.w} + vv * bfpair(kq.w);
;         f32v2 ya = S01 * bfpair(rq.x) + S23 * bfpair(rq.y);
;         f32v2 yb2 = S45 * bfpair(rq.z) + S67 * bfpair(rq.w);
;         ya += yb2;
;         float y = row8_sum(ya.x + ya.y);
;         yd[st * ystride] = y;
;         if (st < 15) { wa = wan; wb = wbn; ka = kan; kb = kbn; ba = ban; bbv = bbn; kq = kqn; rq = rqn; vq = vqn; }
;       }
	ds_read_b128 v[36:39], v101 offset:19968
	ds_read_b128 v[80:83], v101 offset:20736
	v_pk_mul_f32 v[26:27], v[18:19], v[52:53]
	v_pk_mul_f32 v[30:31], v[18:19], v[72:73]
	v_pk_fma_f32 v[26:27], v[20:21], v[54:55], v[26:27]
	v_pk_fma_f32 v[30:31], v[20:21], v[74:75], v[30:31]
	v_add_f32_e32 v28, v26, v27
	v_add_f32_e32 v32, v30, v31
	ds_read_b128 v[48:51], v101 offset:20480
	v_add_f32_dpp v28, v28, v28 quad_perm:[1,0,3,2] row_mask:0xf bank_mask:0xf bound_ctrl:1
	v_add_f32_dpp v32, v32, v32 quad_perm:[1,0,3,2] row_mask:0xf bank_mask:0xf bound_ctrl:1
	ds_read_u16_d16_hi v68, v97 offset:20992
	v_add_f32_dpp v28, v28, v28 quad_perm:[2,3,0,1] row_mask:0xf bank_mask:0xf bound_ctrl:1
	v_add_f32_dpp v32, v32, v32 quad_perm:[2,3,0,1] row_mask:0xf bank_mask:0xf bound_ctrl:1
	ds_read_b128 v[40:43], v101 offset:19712
	v_add_f32_dpp v28, v28, v28 row_half_mirror row_mask:0xf bank_mask:0xf bound_ctrl:1
	v_add_f32_dpp v32, v32, v32 row_half_mirror row_mask:0xf bank_mask:0xf bound_ctrl:1
	ds_read_b128 v[44:47], v101 offset:20224
	v_add_f32_dpp v28, v28, v28 row_mirror row_mask:0xf bank_mask:0xf bound_ctrl:1
	v_add_f32_dpp v32, v32, v32 row_mirror row_mask:0xf bank_mask:0xf bound_ctrl:1
	v_pk_mul_f32 v[34:35], v[70:71], v[64:65] op_sel_hi:[0,1]
	v_pk_mul_f32 v[112:113], v[70:71], v[66:67] op_sel_hi:[0,1]
	v_pk_fma_f32 v[22:23], v[18:19], v[56:57], v[34:35]
	v_pk_fma_f32 v[24:25], v[20:21], v[58:59], v[112:113]
	v_pk_fma_f32 v[18:19], v[28:29], v[60:61], v[22:23] op_sel_hi:[0,1,1] neg_lo:[1,0,0] neg_hi:[1,0,0]
	v_pk_fma_f32 v[20:21], v[28:29], v[62:63], v[24:25] op_sel_hi:[0,1,1] neg_lo:[1,0,0] neg_hi:[1,0,0]
	ds_write_b32 v108, v32 offset:1536
	s_waitcnt lgkmcnt(1)
	ds_read_b128 v[52:55], v101 offset:21376
	ds_read_b128 v[72:75], v101 offset:22144
	v_pk_mul_f32 v[26:27], v[18:19], v[36:37]
	v_pk_mul_f32 v[30:31], v[18:19], v[76:77]
	v_pk_fma_f32 v[26:27], v[20:21], v[38:39], v[26:27]
	v_pk_fma_f32 v[30:31], v[20:21], v[78:79], v[30:31]
	v_add_f32_e32 v28, v26, v27
	v_add_f32_e32 v32, v30, v31
	ds_read_b128 v[64:67], v101 offset:21888
	v_add_f32_dpp v28, v28, v28 quad_perm:[1,0,3,2] row_mask:0xf bank_mask:0xf bound_ctrl:1
	v_add_f32_dpp v32, v32, v32 quad_perm:[1,0,3,2] row_mask:0xf bank_mask:0xf bound_ctrl:1
	ds_read_u16_d16_hi v70, v97 offset:22400
	v_add_f32_dpp v28, v28, v28 quad_perm:[2,3,0,1] row_mask:0xf bank_mask:0xf bound_ctrl:1
	v_add_f32_dpp v32, v32, v32 quad_perm:[2,3,0,1] row_mask:0xf bank_mask:0xf bound_ctrl:1
	ds_read_b128 v[56:59], v101 offset:21120
	v_add_f32_dpp v28, v28, v28 row_half_mirror row_mask:0xf bank_mask:0xf bound_ctrl:1
	v_add_f32_dpp v32, v32, v32 row_half_mirror row_mask:0xf bank_mask:0xf bound_ctrl:1
	ds_read_b128 v[60:63], v101 offset:21632
	v_add_f32_dpp v28, v28, v28 row_mirror row_mask:0xf bank_mask:0xf bound_ctrl:1
	v_add_f32_dpp v32, v32, v32 row_mirror row_mask:0xf bank_mask:0xf bound_ctrl:1
	v_pk_mul_f32 v[34:35], v[68:69], v[48:49] op_sel_hi:[0,1]
	v_pk_mul_f32 v[112:113], v[68:69], v[50:51] op_sel_hi:[0,1]
	v_pk_fma_f32 v[22:23], v[18:19], v[40:41], v[34:35]
	v_pk_fma_f32 v[24:25], v[20:21], v[42:43], v[112:113]
	v_pk_fma_f32 v[18:19], v[28:29], v[44:45], v[22:23] op_sel_hi:[0,1,1] neg_lo:[1,0,0] neg_hi:[1,0,0]
	v_pk_fma_f32 v[20:21], v[28:29], v[46:47], v[24:25] op_sel_hi:[0,1,1] neg_lo:[1,0,0] neg_hi:[1,0,0]
	ds_write_b32 v108, v32 offset:1664
	s_waitcnt lgkmcnt(1)
	v_pk_mul_f32 v[26:27], v[18:19], v[52:53]
	v_pk_mul_f32 v[30:31], v[18:19], v[80:81]
	v_pk_fma_f32 v[26:27], v[20:21], v[54:55], v[26:27]
	v_pk_fma_f32 v[30:31], v[20:21], v[82:83], v[30:31]
	v_add_f32_e32 v28, v26, v27
	v_add_f32_e32 v32, v30, v31
	v_pk_mul_f32 v[34:35], v[70:71], v[64:65] op_sel_hi:[0,1]
	v_add_f32_dpp v28, v28, v28 quad_perm:[1,0,3,2] row_mask:0xf bank_mask:0xf bound_ctrl:1
	v_add_f32_dpp v32, v32, v32 quad_perm:[1,0,3,2] row_mask:0xf bank_mask:0xf bound_ctrl:1
	v_pk_mul_f32 v[112:113], v[70:71], v[66:67] op_sel_hi:[0,1]
	v_add_f32_dpp v28, v28, v28 quad_perm:[2,3,0,1] row_mask:0xf bank_mask:0xf bound_ctrl:1
	v_add_f32_dpp v32, v32, v32 quad_perm:[2,3,0,1] row_mask:0xf bank_mask:0xf bound_ctrl:1
	s_nop 0
	v_add_f32_dpp v28, v28, v28 row_half_mirror row_mask:0xf bank_mask:0xf bound_ctrl:1
	v_add_f32_dpp v32, v32, v32 row_half_mirror row_mask:0xf bank_mask:0xf bound_ctrl:1
	s_nop 0
	v_add_f32_dpp v28, v28, v28 row_mirror row_mask:0xf bank_mask:0xf bound_ctrl:1
	v_add_f32_dpp v32, v32, v32 row_mirror row_mask:0xf bank_mask:0xf bound_ctrl:1
	v_pk_fma_f32 v[22:23], v[18:19], v[56:57], v[34:35]
	v_pk_fma_f32 v[24:25], v[20:21], v[58:59], v[112:113]
	v_pk_fma_f32 v[18:19], v[28:29], v[60:61], v[22:23] op_sel_hi:[0,1,1] neg_lo:[1,0,0] neg_hi:[1,0,0]
	v_pk_fma_f32 v[20:21], v[28:29], v[62:63], v[24:25] op_sel_hi:[0,1,1] neg_lo:[1,0,0] neg_hi:[1,0,0]
	ds_write_b32 v108, v32 offset:1792
	v_pk_mul_f32 v[30:31], v[18:19], v[72:73]
	s_nop 0
	v_pk_fma_f32 v[30:31], v[20:21], v[74:75], v[30:31]
	s_nop 0
	v_add_f32_e32 v32, v30, v31
	s_nop 1
	v_add_f32_dpp v32, v32, v32 quad_perm:[1,0,3,2] row_mask:0xf bank_mask:0xf bound_ctrl:1
	s_nop 1
	v_add_f32_dpp v32, v32, v32 quad_perm:[2,3,0,1] row_mask:0xf bank_mask:0xf bound_ctrl:1
	s_nop 1
	v_add_f32_dpp v32, v32, v32 row_half_mirror row_mask:0xf bank_mask:0xf bound_ctrl:1
	s_nop 1
	v_add_f32_dpp v32, v32, v32 row_mirror row_mask:0xf bank_mask:0xf bound_ctrl:1
	ds_write_b32 v108, v32 offset:1920
	v_add_u32_e32 v100, 16, v100
	s_waitcnt vmcnt(4)
	s_cmp_eq_u32 s27, 0
	s_cbranch_scc1 .Lrw_w2_h1
	s_cmp_lg_u32 s27, 0xfe
	s_cbranch_scc1 .Lrw_w4_h1

; DI f32v2 bfpair(unsigned q) { f32v2 r; r.x = __uint_as_float(q << 16); r.y = __uint_as_float(q & 0xffff0000u); return r; }
; DI void rwkv_scan_item(const PRef& p, int b, int h, int half) {
;     ...
;       for (int st = 0; st < 16; ++st) {
;         float4 wan, wbn, kan, kbn, ban, bbn; uint4 kqn, rqn; unsigned vqn;
;         if (st < 15) {
;           const char* sn = cb + (st + 1) * 1152;
;           wan = *reinterpret_cast<const float4*>(sn + ks * 4); wbn = *reinterpret_cast<const float4*>(sn + ks * 4 + 16);
;           kan = *reinterpret_cast<const float4*>(sn + 256 + ks * 4); kbn = *reinterpret_cast<const float4*>(sn + 256 + ks * 4 + 16);
;           ban = *reinterpret_cast<const float4*>(sn + 512 + ks * 4); bbn = *reinterpret_cast<const float4*>(sn + 512 + ks * 4 + 16);
;           kqn = *reinterpret_cast<const uint4*>(sn + 768 + ks * 2);
;           rqn = *reinterpret_cast<const uint4*>(sn + 896 + ks * 2);
;           vqn = *reinterpret_cast<const u16*>(sn + 1024 + row * 2);
;         }
;         const float v = __uint_as_float(vq << 16);
;         const f32v2 vv = {v, v};
;         const f32v2 kk01 = {ka.x, ka.y}, kk23 = {ka.z, ka.w}, kk45 = {kb.x, kb.y}, kk67 = {kb.z, kb.w};
;         f32v2 sa2 = S01 * kk01 + S23 * kk23;
;         f32v2 sb2 = S45 * kk45 + S67 * kk67;
;         sa2 += sb2;
;         float sa = row8_sum(sa2.x + sa2.y);
;         const f32v2 sav = {sa, sa};
;         S01 = S01 * f32v2{wa.x, wa.y} - sav * f32v2{ba.x, ba.y} + vv * bfpair(kq.x);
;         S23 = S23 * f32v2{wa.z, wa.w} - sav * f32v2{ba.z, ba.w} + vv * bfpair(kq.y);
;         S45 = S45 * f32v2{wb.x, wb.y} - sav * f32v2{bbv.x, bbv.y} + vv * bfpair(kq.z);
;         S67 = S67 * f32v2{wb.z, wb.w} - sav * f32v2{bbv.z, bbv.w} + vv * bfpair(kq.w);
;         f32v2 ya = S01 * bfpair(rq.x) + S23 * bfpair(rq.y);
;         f32v2 yb2 = S45 * bfpair(rq.z) + S67 * bfpair(rq.w);
;         ya += yb2;
;         float y = row8_sum(ya.x + ya.y);
;         yd[st * ystride] = y;
.Lrw_compute_h1:
	ds_read_b128 v[36:39], v121 offset:256
	ds_read_b128 v[72:75], v121 offset:1024
	ds_read_b128 v[48:51], v121 offset:768
	ds_read_u16_d16_hi v68, v122 offset:1280
	ds_read_b128 v[40:43], v121 offset:0
	ds_read_b128 v[44:47], v121 offset:512
	s_waitcnt lgkmcnt(0)
	v_pk_mul_f32 v[26:27], v[18:19], v[36:37]
	s_nop 0
	v_pk_fma_f32 v[26:27], v[20:21], v[38:39], v[26:27]
	s_nop 0
	v_add_f32_e32 v28, v26, v27
	ds_read_b128 v[52:55], v121 offset:1664
	ds_read_b128 v[76:79], v121 offset:2432
	v_add_f32_dpp v28, v28, v28 quad_perm:[1,0,3,2] row_mask:0xf bank_mask:0xf bound_ctrl:1
	ds_read_b128 v[64:67], v121 offset:2176
	ds_read_u16_d16_hi v70, v122 offset:2688
	v_add_f32_dpp v28, v28, v28 quad_perm:[2,3,0,1] row_mask:0xf bank_mask:0xf bound_ctrl:1
	ds_read_b128 v[56:59], v121 offset:1408
	ds_read_b128 v[60:63], v121 offset:1920
	v_add_f32_dpp v28, v28, v28 row_half_mirror row_mask:0xf bank_mask:0xf bound_ctrl:1
	v_pk_mul_f32 v[34:35], v[68:69], v[48:49] op_sel_hi:[0,1]
	v_pk_mul_f32 v[112:113], v[68:69], v[50:51] op_sel_hi:[0,1]
	v_add_f32_dpp v28, v28, v28 row_mirror row_mask:0xf bank_mask:0xf bound_ctrl:1
	v_pk_fma_f32 v[22:23], v[18:19], v[40:41], v[34:35]
	v_pk_fma_f32 v[24:25], v[20:21], v[42:43], v[112:113]
	v_pk_fma_f32 v[18:19], v[28:29], v[44:45], v[22:23] op_sel_hi:[0,1,1] neg_lo:[1,0,0] neg_hi:[1,0,0]
	v_pk_fma_f32 v[20:21], v[28:29], v[46:47], v[24:25] op_sel_hi:[0,1,1] neg_lo:[1,0,0] neg_hi:[1,0,0]
	s_waitcnt lgkmcnt(0)
	ds_read_b128 v[36:39], v121 offset:3072
	ds_read_b128 v[80:83], v121 offset:3840
	v_pk_mul_f32 v[26:27], v[18:19], v[52:53]
	v_pk_mul_f32 v[30:31], v[18:19], v[72:73]
	v_pk_fma_f32 v[26:27], v[20:21], v[54:55], v[26:27]
	v_pk_fma_f32 v[30:31], v[20:21], v[74:75], v[30:31]
	v_add_f32_e32 v28, v26, v27
	v_add_f32_e32 v32, v30, v31
	ds_read_b128 v[48:51], v121 offset:3584
	v_add_f32_dpp v28, v28, v28 quad_perm:[1,0,3,2] row_mask:0xf bank_mask:0xf bound_ctrl:1
	v_add_f32_dpp v32, v32, v32 quad_perm:[1,0,3,2] row_mask:0xf bank_mask:0xf bound_ctrl:1
	ds_read_u16_d16_hi v68, v122 offset:4096
	v_add_f32_dpp v28, v28, v28 quad_perm:[2,3,0,1] row_mask:0xf bank_mask:0xf bound_ctrl:1
	v_add_f32_dpp v32, v32, v32 quad_perm:[2,3,0,1] row_mask:0xf bank_mask:0xf bound_ctrl:1
	ds_read_b128 v[40:43], v121 offset:2816
	v_add_f32_dpp v28, v28, v28 row_half_mirror row_mask:0xf bank_mask:0xf bound_ctrl:1
	v_add_f32_dpp v32, v32, v32 row_half_mirror row_mask:0xf bank_mask:0xf bound_ctrl:1
	ds_read_b128 v[44:47], v121 offset:3328
	v_add_f32_dpp v28, v28, v28 row_mirror row_mask:0xf bank_mask:0xf bound_ctrl:1
	v_add_f32_dpp v32, v32, v32 row_mirror row_mask:0xf bank_mask:0xf bound_ctrl:1
	v_pk_mul_f32 v[34:35], v[70:71], v[64:65] op_sel_hi:[0,1]
	v_pk_mul_f32 v[112:113], v[70:71], v[66:67] op_sel_hi:[0,1]
	v_pk_fma_f32 v[22:23], v[18:19], v[56:57], v[34:35]
	v_pk_fma_f32 v[24:25], v[20:21], v[58:59], v[112:113]
	v_pk_fma_f32 v[18:19], v[28:29], v[60:61], v[22:23] op_sel_hi:[0,1,1] neg_lo:[1,0,0] neg_hi:[1,0,0]
	v_pk_fma_f32 v[20:21], v[28:29], v[62:63], v[24:25] op_sel_hi:[0,1,1] neg_lo:[1,0,0] neg_hi:[1,0,0]
	ds_write_b32 v148, v32 offset:0
	s_waitcnt lgkmcnt(1)
	ds_read_b128 v[52:55], v121 offset:4480
	ds_read_b128 v[72:75], v121 offset:5248
	v_pk_mul_f32 v[26:27], v[18:19], v[36:37]
	v_pk_mul_f32 v[30:31], v[18:19], v[76:77]
	v_pk_fma_f32 v[26:27], v[20:21], v[38:39], v[26:27]
	v_pk_fma_f32 v[30:31], v[20:21], v[78:79], v[30:31]
	v_add_f32_e32 v28, v26, v27
	v_add_f32_e32 v32, v30, v31
	ds_read_b128 v[64:67], v121 offset:4992
	v_add_f32_dpp v28, v28, v28 quad_perm:[1,0,3,2] row_mask:0xf bank_mask:0xf bound_ctrl:1
	v_add_f32_dpp v32, v32, v32 quad_perm:[1,0,3,2] row_mask:0xf bank_mask:0xf bound_ctrl:1
	ds_read_u16_d16_hi v70, v122 offset:5504
	v_add_f32_dpp v28, v28, v28 quad_perm:[2,3,0,1] row_mask:0xf bank_mask:0xf bound_ctrl:1
	v_add_f32_dpp v32, v32, v32 quad_perm:[2,3,0,1] row_mask:0xf bank_mask:0xf bound_ctrl:1
	ds_read_b128 v[56:59], v121 offset:4224
	v_add_f32_dpp v28, v28, v28 row_half_mirror row_mask:0xf bank_mask:0xf bound_ctrl:1
	v_add_f32_dpp v32, v32, v32 row_half_mirror row_mask:0xf bank_mask:0xf bound_ctrl:1
	ds_read_b128 v[60:63], v121 offset:4736
	v_add_f32_dpp v28, v28, v28 row_mirror row_mask:0xf bank_mask:0xf bound_ctrl:1
	v_add_f32_dpp v32, v32, v32 row_mirror row_mask:0xf bank_mask:0xf bound_ctrl:1
	v_pk_mul_f32 v[34:35], v[68:69], v[48:49] op_sel_hi:[0,1]
	v_pk_mul_f32 v[112:113], v[68:69], v[50:51] op_sel_hi:[0,1]
	v_pk_fma_f32 v[22:23], v[18:19], v[40:41], v[34:35]
	v_pk_fma_f32 v[24:25], v[20:21], v[42:43], v[112:113]
	v_pk_fma_f32 v[18:19], v[28:29], v[44:45], v[22:23] op_sel_hi:[0,1,1] neg_lo:[1,0,0] neg_hi:[1,0,0]
	v_pk_fma_f32 v[20:21], v[28:29], v[46:47], v[24:25] op_sel_hi:[0,1,1] neg_lo:[1,0,0] neg_hi:[1,0,0]
	ds_write_b32 v148, v32 offset:128
	s_waitcnt lgkmcnt(1)
	ds_read_b128 v[36:39], v121 offset:5888
	ds_read_b128 v[76:79], v121 offset:6656
	v_pk_mul_f32 v[26:27], v[18:19], v[52:53]
	v_pk_mul_f32 v[30:31], v[18:19], v[80:81]
	v_pk_fma_f32 v[26:27], v[20:21], v[54:55], v[26:27]
	v_pk_fma_f32 v[30:31], v[20:21], v[82:83], v[30:31]
	v_add_f32_e32 v28, v26, v27
	v_add_f32_e32 v32, v30, v31
	ds_read_b128 v[48:51], v121 offset:6400
	v_add_f32_dpp v28, v28, v28 quad_perm:[1,0,3,2] row_mask:0xf bank_mask:0xf bound_ctrl:1
	v_add_f32_dpp v32, v32, v32 quad_perm:[1,0,3,2] row_mask:0xf bank_mask:0xf bound_ctrl:1
	ds_read_u16_d16_hi v68, v122 offset:6912
	v_add_f32_dpp v28, v28, v28 quad_perm:[2,3,0,1] row_mask:0xf bank_mask:0xf bound_ctrl:1
	v_add_f32_dpp v32, v32, v32 quad_perm:[2,3,0,1] row_mask:0xf bank_mask:0xf bound_ctrl:1
	ds_read_b128 v[40:43], v121 offset:5632
	v_add_f32_dpp v28, v28, v28 row_half_mirror row_mask:0xf bank_mask:0xf bound_ctrl:1
	v_add_f32_dpp v32, v32, v32 row_half_mirror row_mask:0xf bank_mask:0xf bound_ctrl:1
	ds_read_b128 v[44:47], v121 offset:6144
	v_add_f32_dpp v28, v28, v28 row_mirror row_mask:0xf bank_mask:0xf bound_ctrl:1
	v_add_f32_dpp v32, v32, v32 row_mirror row_mask:0xf bank_mask:0xf bound_ctrl:1
	v_pk_mul_f32 v[34:35], v[70:71], v[64:65] op_sel_hi:[0,1]
	v_pk_mul_f32 v[112:113], v[70:71], v[66:67] op_sel_hi:[0,1]
	v_pk_fma_f32 v[22:23], v[18:19], v[56:57], v[34:35]
	v_pk_fma_f32 v[24:25], v[20:21], v[58:59], v[112:113]
	v_pk_fma_f32 v[18:19], v[28:29], v[60:61], v[22:23] op_sel_hi:[0,1,1] neg_lo:[1,0,0] neg_hi:[1,0,0]
	v_pk_fma_f32 v[20:21], v[28:29], v[62:63], v[24:25] op_sel_hi:[0,1,1] neg_lo:[1,0,0] neg_hi:[1,0,0]
	ds_write_b32 v148, v32 offset:256
	s_waitcnt lgkmcnt(1)
; DI f32v2 bfpair(unsigned q) { f32v2 r; r.x = __uint_as_float(q << 16); r.y = __uint_as_float(q & 0xffff0000u); return r; }
; DI void rwkv_scan_item(const PRef& p, int b, int h, int half) {
;     ...
;       for (int st = 0; st < 16; ++st) {
;         float4 wan, wbn, kan, kbn, ban, bbn; uint4 kqn, rqn; unsigned vqn;
;         if (st < 15) {
;           const char* sn = cb + (st + 1) * 1152;
;           wan = *reinterpret_cast<const float4*>(sn + ks * 4); wbn = *reinterpret_cast<const float4*>(sn + ks * 4 + 16);
;           kan = *reinterpret_cast<const float4*>(sn + 256 + ks * 4); kbn = *reinterpret_cast<const float4*>(sn + 256 + ks * 4 + 16);
;           ban = *reinterpret_cast<const float4*>(sn + 512 + ks * 4); bbn = *reinterpret_cast<const float4*>(sn + 512 + ks * 4 + 16);
;           kqn = *reinterpret_cast<const uint4*>(sn + 768 + ks * 2);
;           rqn = *reinterpret_cast<const uint4*>(sn + 896 + ks * 2);
;           vqn = *reinterpret_cast<const u16*>(sn + 1024 + row * 2);
;         }
;         const float v = __uint_as_float(vq << 16);
;         const f32v2 vv = {v, v};
;         const f32v2 kk01 = {ka.x, ka.y}, kk23 = {ka.z, ka.w}, kk45 = {kb.x, kb.y}, kk67 = {kb.z, kb.w};
;         f32v2 sa2 = S01 * kk01 + S23 * kk23;
;         f32v2 sb2 = S45 * kk45 + S67 * kk67;
;         sa2 += sb2;
;         float sa = row8_sum(sa2.x + sa2.y);
;         const f32v2 sav = {sa, sa};
;         S01 = S01 * f32v2{wa.x, wa.y} - sav * f32v2{ba.x, ba.y} + vv * bfpair(kq.x);
;         S23 = S23 * f32v2{wa.z, wa.w} - sav * f32v2{ba.z, ba.w} + vv * bfpair(kq.y);
;         S45 = S45 * f32v2{wb.x, wb.y} - sav * f32v2{bbv.x, bbv.y} + vv * bfpair(kq.z);
;         S67 = S67 * f32v2{wb.z, wb.w} - sav * f32v2{bbv.z, bbv.w} + vv * bfpair(kq.w);
;         f32v2 ya = S01 * bfpair(rq.x) + S23 * bfpair(rq.y);
;         f32v2 yb2 = S45 * bfpair(rq.z) + S67 * bfpair(rq.w);
;         ya += yb2;
;         float y = row8_sum(ya.x + ya.y);
;         yd[st * ystride] = y;
	ds_read_b128 v[52:55], v121 offset:7296
	ds_read_b128 v[80:83], v121 offset:8064
	v_pk_mul_f32 v[26:27], v[18:19], v[36:37]
	v_pk_mul_f32 v[30:31], v[18:19], v[72:73]
	v_pk_fma_f32 v[26:27], v[20:21], v[38:39], v[26:27]
	v_pk_fma_f32 v[30:31], v[20:21], v[74:75], v[30:31]
	v_add_f32_e32 v28, v26, v27
	v_add_f32_e32 v32, v30, v31
	ds_read_b128 v[64:67], v121 offset:7808
	v_add_f32_dpp v28, v28, v28 quad_perm:[1,0,3,2] row_mask:0xf bank_mask:0xf bound_ctrl:1
	v_add_f32_dpp v32, v32, v32 quad_perm:[1,0,3,2] row_mask:0xf bank_mask:0xf bound_ctrl:1
	ds_read_u16_d16_hi v70, v122 offset:8320
	v_add_f32_dpp v28, v28, v28 quad_perm:[2,3,0,1] row_mask:0xf bank_mask:0xf bound_ctrl:1
	v_add_f32_dpp v32, v32, v32 quad_perm:[2,3,0,1] row_mask:0xf bank_mask:0xf bound_ctrl:1
	ds_read_b128 v[56:59], v121 offset:7040
	v_add_f32_dpp v28, v28, v28 row_half_mirror row_mask:0xf bank_mask:0xf bound_ctrl:1
	v_add_f32_dpp v32, v32, v32 row_half_mirror row_mask:0xf bank_mask:0xf bound_ctrl:1
	ds_read_b128 v[60:63], v121 offset:7552
	v_add_f32_dpp v28, v28, v28 row_mirror row_mask:0xf bank_mask:0xf bound_ctrl:1
	v_add_f32_dpp v32, v32, v32 row_mirror row_mask:0xf bank_mask:0xf bound_ctrl:1
	v_pk_mul_f32 v[34:35], v[68:69], v[48:49] op_sel_hi:[0,1]
	v_pk_mul_f32 v[112:113], v[68:69], v[50:51] op_sel_hi:[0,1]
	v_pk_fma_f32 v[22:23], v[18:19], v[40:41], v[34:35]
	v_pk_fma_f32 v[24:25], v[20:21], v[42:43], v[112:113]
	v_pk_fma_f32 v[18:19], v[28:29], v[44:45], v[22:23] op_sel_hi:[0,1,1] neg_lo:[1,0,0] neg_hi:[1,0,0]
	v_pk_fma_f32 v[20:21], v[28:29], v[46:47], v[24:25] op_sel_hi:[0,1,1] neg_lo:[1,0,0] neg_hi:[1,0,0]
	ds_write_b32 v148, v32 offset:384
	s_waitcnt lgkmcnt(1)
	ds_read_b128 v[36:39], v121 offset:8704
	ds_read_b128 v[72:75], v121 offset:9472
	v_pk_mul_f32 v[26:27], v[18:19], v[52:53]
	v_pk_mul_f32 v[30:31], v[18:19], v[76:77]
	v_pk_fma_f32 v[26:27], v[20:21], v[54:55], v[26:27]
	v_pk_fma_f32 v[30:31], v[20:21], v[78:79], v[30:31]
	v_add_f32_e32 v28, v26, v27
	v_add_f32_e32 v32, v30, v31
	ds_read_b128 v[48:51], v121 offset:9216
	v_add_f32_dpp v28, v28, v28 quad_perm:[1,0,3,2] row_mask:0xf bank_mask:0xf bound_ctrl:1
	v_add_f32_dpp v32, v32, v32 quad_perm:[1,0,3,2] row_mask:0xf bank_mask:0xf bound_ctrl:1
	ds_read_u16_d16_hi v68, v122 offset:9728
	v_add_f32_dpp v28, v28, v28 quad_perm:[2,3,0,1] row_mask:0xf bank_mask:0xf bound_ctrl:1
	v_add_f32_dpp v32, v32, v32 quad_perm:[2,3,0,1] row_mask:0xf bank_mask:0xf bound_ctrl:1
	ds_read_b128 v[40:43], v121 offset:8448
	v_add_f32_dpp v28, v28, v28 row_half_mirror row_mask:0xf bank_mask:0xf bound_ctrl:1
	v_add_f32_dpp v32, v32, v32 row_half_mirror row_mask:0xf bank_mask:0xf bound_ctrl:1
	ds_read_b128 v[44:47], v121 offset:8960
	v_add_f32_dpp v28, v28, v28 row_mirror row_mask:0xf bank_mask:0xf bound_ctrl:1
	v_add_f32_dpp v32, v32, v32 row_mirror row_mask:0xf bank_mask:0xf bound_ctrl:1
	v_pk_mul_f32 v[34:35], v[70:71], v[64:65] op_sel_hi:[0,1]
	v_pk_mul_f32 v[112:113], v[70:71], v[66:67] op_sel_hi:[0,1]
	v_pk_fma_f32 v[22:23], v[18:19], v[56:57], v[34:35]
	v_pk_fma_f32 v[24:25], v[20:21], v[58:59], v[112:113]
	v_pk_fma_f32 v[18:19], v[28:29], v[60:61], v[22:23] op_sel_hi:[0,1,1] neg_lo:[1,0,0] neg_hi:[1,0,0]
	v_pk_fma_f32 v[20:21], v[28:29], v[62:63], v[24:25] op_sel_hi:[0,1,1] neg_lo:[1,0,0] neg_hi:[1,0,0]
	ds_write_b32 v148, v32 offset:512
	s_waitcnt lgkmcnt(1)
	ds_read_b128 v[52:55], v121 offset:10112
	ds_read_b128 v[76:79], v121 offset:10880
	v_pk_mul_f32 v[26:27], v[18:19], v[36:37]
	v_pk_mul_f32 v[30:31], v[18:19], v[80:81]
	v_pk_fma_f32 v[26:27], v[20:21], v[38:39], v[26:27]
	v_pk_fma_f32 v[30:31], v[20:21], v[82:83], v[30:31]
	v_add_f32_e32 v28, v26, v27
	v_add_f32_e32 v32, v30, v31
	ds_read_b128 v[64:67], v121 offset:10624
	v_add_f32_dpp v28, v28, v28 quad_perm:[1,0,3,2] row_mask:0xf bank_mask:0xf bound_ctrl:1
	v_add_f32_dpp v32, v32, v32 quad_perm:[1,0,3,2] row_mask:0xf bank_mask:0xf bound_ctrl:1
	ds_read_u16_d16_hi v70, v122 offset:11136
	v_add_f32_dpp v28, v28, v28 quad_perm:[2,3,0,1] row_mask:0xf bank_mask:0xf bound_ctrl:1
	v_add_f32_dpp v32, v32, v32 quad_perm:[2,3,0,1] row_mask:0xf bank_mask:0xf bound_ctrl:1
	ds_read_b128 v[56:59], v121 offset:9856
	v_add_f32_dpp v28, v28, v28 row_half_mirror row_mask:0xf bank_mask:0xf bound_ctrl:1
	v_add_f32_dpp v32, v32, v32 row_half_mirror row_mask:0xf bank_mask:0xf bound_ctrl:1
	ds_read_b128 v[60:63], v121 offset:10368
	v_add_f32_dpp v28, v28, v28 row_mirror row_mask:0xf bank_mask:0xf bound_ctrl:1
	v_add_f32_dpp v32, v32, v32 row_mirror row_mask:0xf bank_mask:0xf bound_ctrl:1
	v_pk_mul_f32 v[34:35], v[68:69], v[48:49] op_sel_hi:[0,1]
	v_pk_mul_f32 v[112:113], v[68:69], v[50:51] op_sel_hi:[0,1]
	v_pk_fma_f32 v[22:23], v[18:19], v[40:41], v[34:35]
	v_pk_fma_f32 v[24:25], v[20:21], v[42:43], v[112:113]
	v_pk_fma_f32 v[18:19], v[28:29], v[44:45], v[22:23] op_sel_hi:[0,1,1] neg_lo:[1,0,0] neg_hi:[1,0,0]
	v_pk_fma_f32 v[20:21], v[28:29], v[46:47], v[24:25] op_sel_hi:[0,1,1] neg_lo:[1,0,0] neg_hi:[1,0,0]
	ds_write_b32 v148, v32 offset:640
	s_waitcnt lgkmcnt(1)
; DI f32v2 bfpair(unsigned q) { f32v2 r; r.x = __uint_as_float(q << 16); r.y = __uint_as_float(q & 0xffff0000u); return r; }
; DI void rwkv_scan_item(const PRef& p, int b, int h, int half) {
;     ...
;       for (int st = 0; st < 16; ++st) {
;         float4 wan, wbn, kan, kbn, ban, bbn; uint4 kqn, rqn; unsigned vqn;
;         if (st < 15) {
;           const char* sn = cb + (st + 1) * 1152;
;           wan = *reinterpret_cast<const float4*>(sn + ks * 4); wbn = *reinterpret_cast<const float4*>(sn + ks * 4 + 16);
;           kan = *reinterpret_cast<const float4*>(sn + 256 + ks * 4); kbn = *reinterpret_cast<const float4*>(sn + 256 + ks * 4 + 16);
;           ban = *reinterpret_cast<const float4*>(sn + 512 + ks * 4); bbn = *reinterpret_cast<const float4*>(sn + 512 + ks * 4 + 16);
;           kqn = *reinterpret_cast<const uint4*>(sn + 768 + ks * 2);
;           rqn = *reinterpret_cast<const uint4*>(sn + 896 + ks * 2);
;           vqn = *reinterpret_cast<const u16*>(sn + 1024 + row * 2);
;         }
;         const float v = __uint_as_float(vq << 16);
;         const f32v2 vv = {v, v};
;         const f32v2 kk01 = {ka.x, ka.y}, kk23 = {ka.z, ka.w}, kk45 = {kb.x, kb.y}, kk67 = {kb.z, kb.w};
;         f32v2 sa2 = S01 * kk01 + S23 * kk23;
;         f32v2 sb2 = S45 * kk45 + S67 * kk67;
;         sa2 += sb2;
;         float sa = row8_sum(sa2.x + sa2.y);
;         const f32v2 sav = {sa, sa};
;         S01 = S01 * f32v2{wa.x, wa.y} - sav * f32v2{ba.x, ba.y} + vv * bfpair(kq.x);
;         S23 = S23 * f32v2{wa.z, wa.w} - sav * f32v2{ba.z, ba.w} + vv * bfpair(kq.y);
;         S45 = S45 * f32v2{wb.x, wb.y} - sav * f32v2{bbv.x, bbv.y} + vv * bfpair(kq.z);
;         S67 = S67 * f32v2{wb.z, wb.w} - sav * f32v2{bbv.z, bbv.w} + vv * bfpair(kq.w);
;         f32v2 ya = S01 * bfpair(rq.x) + S23 * bfpair(rq.y);
;         f32v2 yb2 = S45 * bfpair(rq.z) + S67 * bfpair(rq.w);
;         ya += yb2;
;         float y = row8_sum(ya.x + ya.y);
;         yd[st * ystride] = y;
	ds_read_b128 v[36:39], v121 offset:11520
	ds_read_b128 v[80:83], v121 offset:12288
	v_pk_mul_f32 v[26:27], v[18:19], v[52:53]
	v_pk_mul_f32 v[30:31], v[18:19], v[72:73]
	v_pk_fma_f32 v[26:27], v[20:21], v[54:55], v[26:27]
	v_pk_fma_f32 v[30:31], v[20:21], v[74:75], v[30:31]
	v_add_f32_e32 v28, v26, v27
	v_add_f32_e32 v32, v30, v31
	ds_read_b128 v[48:51], v121 offset:12032
	v_add_f32_dpp v28, v28, v28 quad_perm:[1,0,3,2] row_mask:0xf bank_mask:0xf bound_ctrl:1
	v_add_f32_dpp v32, v32, v32 quad_perm:[1,0,3,2] row_mask:0xf bank_mask:0xf bound_ctrl:1
	ds_read_u16_d16_hi v68, v122 offset:12544
	v_add_f32_dpp v28, v28, v28 quad_perm:[2,3,0,1] row_mask:0xf bank_mask:0xf bound_ctrl:1
	v_add_f32_dpp v32, v32, v32 quad_perm:[2,3,0,1] row_mask:0xf bank_mask:0xf bound_ctrl:1
	ds_read_b128 v[40:43], v121 offset:11264
	v_add_f32_dpp v28, v28, v28 row_half_mirror row_mask:0xf bank_mask:0xf bound_ctrl:1
	v_add_f32_dpp v32, v32, v32 row_half_mirror row_mask:0xf bank_mask:0xf bound_ctrl:1
	ds_read_b128 v[44:47], v121 offset:11776
	v_add_f32_dpp v28, v28, v28 row_mirror row_mask:0xf bank_mask:0xf bound_ctrl:1
	v_add_f32_dpp v32, v32, v32 row_mirror row_mask:0xf bank_mask:0xf bound_ctrl:1
	v_pk_mul_f32 v[34:35], v[70:71], v[64:65] op_sel_hi:[0,1]
	v_pk_mul_f32 v[112:113], v[70:71], v[66:67] op_sel_hi:[0,1]
	v_pk_fma_f32 v[22:23], v[18:19], v[56:57], v[34:35]
	v_pk_fma_f32 v[24:25], v[20:21], v[58:59], v[112:113]
	v_pk_fma_f32 v[18:19], v[28:29], v[60:61], v[22:23] op_sel_hi:[0,1,1] neg_lo:[1,0,0] neg_hi:[1,0,0]
	v_pk_fma_f32 v[20:21], v[28:29], v[62:63], v[24:25] op_sel_hi:[0,1,1] neg_lo:[1,0,0] neg_hi:[1,0,0]
	ds_write_b32 v148, v32 offset:768
	s_waitcnt lgkmcnt(1)
	ds_read_b128 v[52:55], v121 offset:12928
	ds_read_b128 v[72:75], v121 offset:13696
	v_pk_mul_f32 v[26:27], v[18:19], v[36:37]
	v_pk_mul_f32 v[30:31], v[18:19], v[76:77]
	v_pk_fma_f32 v[26:27], v[20:21], v[38:39], v[26:27]
	v_pk_fma_f32 v[30:31], v[20:21], v[78:79], v[30:31]
	v_add_f32_e32 v28, v26, v27
	v_add_f32_e32 v32, v30, v31
	ds_read_b128 v[64:67], v121 offset:13440
	v_add_f32_dpp v28, v28, v28 quad_perm:[1,0,3,2] row_mask:0xf bank_mask:0xf bound_ctrl:1
	v_add_f32_dpp v32, v32, v32 quad_perm:[1,0,3,2] row_mask:0xf bank_mask:0xf bound_ctrl:1
	ds_read_u16_d16_hi v70, v122 offset:13952
	v_add_f32_dpp v28, v28, v28 quad_perm:[2,3,0,1] row_mask:0xf bank_mask:0xf bound_ctrl:1
	v_add_f32_dpp v32, v32, v32 quad_perm:[2,3,0,1] row_mask:0xf bank_mask:0xf bound_ctrl:1
	ds_read_b128 v[56:59], v121 offset:12672
	v_add_f32_dpp v28, v28, v28 row_half_mirror row_mask:0xf bank_mask:0xf bound_ctrl:1
	v_add_f32_dpp v32, v32, v32 row_half_mirror row_mask:0xf bank_mask:0xf bound_ctrl:1
	ds_read_b128 v[60:63], v121 offset:13184
	v_add_f32_dpp v28, v28, v28 row_mirror row_mask:0xf bank_mask:0xf bound_ctrl:1
	v_add_f32_dpp v32, v32, v32 row_mirror row_mask:0xf bank_mask:0xf bound_ctrl:1
	v_pk_mul_f32 v[34:35], v[68:69], v[48:49] op_sel_hi:[0,1]
	v_pk_mul_f32 v[112:113], v[68:69], v[50:51] op_sel_hi:[0,1]
	v_pk_fma_f32 v[22:23], v[18:19], v[40:41], v[34:35]
	v_pk_fma_f32 v[24:25], v[20:21], v[42:43], v[112:113]
	v_pk_fma_f32 v[18:19], v[28:29], v[44:45], v[22:23] op_sel_hi:[0,1,1] neg_lo:[1,0,0] neg_hi:[1,0,0]
	v_pk_fma_f32 v[20:21], v[28:29], v[46:47], v[24:25] op_sel_hi:[0,1,1] neg_lo:[1,0,0] neg_hi:[1,0,0]
	ds_write_b32 v148, v32 offset:896
	s_waitcnt lgkmcnt(1)
	ds_read_b128 v[36:39], v121 offset:14336
	ds_read_b128 v[76:79], v121 offset:15104
	v_pk_mul_f32 v[26:27], v[18:19], v[52:53]
	v_pk_mul_f32 v[30:31], v[18:19], v[80:81]
	v_pk_fma_f32 v[26:27], v[20:21], v[54:55], v[26:27]
	v_pk_fma_f32 v[30:31], v[20:21], v[82:83], v[30:31]
	v_add_f32_e32 v28, v26, v27
	v_add_f32_e32 v32, v30, v31
	ds_read_b128 v[48:51], v121 offset:14848
	v_add_f32_dpp v28, v28, v28 quad_perm:[1,0,3,2] row_mask:0xf bank_mask:0xf bound_ctrl:1
	v_add_f32_dpp v32, v32, v32 quad_perm:[1,0,3,2] row_mask:0xf bank_mask:0xf bound_ctrl:1
	ds_read_u16_d16_hi v68, v122 offset:15360
	v_add_f32_dpp v28, v28, v28 quad_perm:[2,3,0,1] row_mask:0xf bank_mask:0xf bound_ctrl:1
	v_add_f32_dpp v32, v32, v32 quad_perm:[2,3,0,1] row_mask:0xf bank_mask:0xf bound_ctrl:1
	ds_read_b128 v[40:43], v121 offset:14080
	v_add_f32_dpp v28, v28, v28 row_half_mirror row_mask:0xf bank_mask:0xf bound_ctrl:1
	v_add_f32_dpp v32, v32, v32 row_half_mirror row_mask:0xf bank_mask:0xf bound_ctrl:1
	ds_read_b128 v[44:47], v121 offset:14592
	v_add_f32_dpp v28, v28, v28 row_mirror row_mask:0xf bank_mask:0xf bound_ctrl:1
	v_add_f32_dpp v32, v32, v32 row_mirror row_mask:0xf bank_mask:0xf bound_ctrl:1
	v_pk_mul_f32 v[34:35], v[70:71], v[64:65] op_sel_hi:[0,1]
	v_pk_mul_f32 v[112:113], v[70:71], v[66:67] op_sel_hi:[0,1]
	v_pk_fma_f32 v[22:23], v[18:19], v[56:57], v[34:35]
	v_pk_fma_f32 v[24:25], v[20:21], v[58:59], v[112:113]
	v_pk_fma_f32 v[18:19], v[28:29], v[60:61], v[22:23] op_sel_hi:[0,1,1] neg_lo:[1,0,0] neg_hi:[1,0,0]
	v_pk_fma_f32 v[20:21], v[28:29], v[62:63], v[24:25] op_sel_hi:[0,1,1] neg_lo:[1,0,0] neg_hi:[1,0,0]
	ds_write_b32 v148, v32 offset:1024
	s_waitcnt lgkmcnt(1)
; DI f32v2 bfpair(unsigned q) { f32v2 r; r.x = __uint_as_float(q << 16); r.y = __uint_as_float(q & 0xffff0000u); return r; }
; DI void rwkv_scan_item(const PRef& p, int b, int h, int half) {
;     ...
;       for (int st = 0; st < 16; ++st) {
;         float4 wan, wbn, kan, kbn, ban, bbn; uint4 kqn, rqn; unsigned vqn;
;         if (st < 15) {
;           const char* sn = cb + (st + 1) * 1152;
;           wan = *reinterpret_cast<const float4*>(sn + ks * 4); wbn = *reinterpret_cast<const float4*>(sn + ks * 4 + 16);
;           kan = *reinterpret_cast<const float4*>(sn + 256 + ks * 4); kbn = *reinterpret_cast<const float4*>(sn + 256 + ks * 4 + 16);
;           ban = *reinterpret_cast<const float4*>(sn + 512 + ks * 4); bbn = *reinterpret_cast<const float4*>(sn + 512 + ks * 4 + 16);
;           kqn = *reinterpret_cast<const uint4*>(sn + 768 + ks * 2);
;           rqn = *reinterpret_cast<const uint4*>(sn + 896 + ks * 2);
;           vqn = *reinterpret_cast<const u16*>(sn + 1024 + row * 2);
;         }
;         const float v = __uint_as_float(vq << 16);
;         const f32v2 vv = {v, v};
;         const f32v2 kk01 = {ka.x, ka.y}, kk23 = {ka.z, ka.w}, kk45 = {kb.x, kb.y}, kk67 = {kb.z, kb.w};
;         f32v2 sa2 = S01 * kk01 + S23 * kk23;
;         f32v2 sb2 = S45 * kk45 + S67 * kk67;
;         sa2 += sb2;
;         float sa = row8_sum(sa2.x + sa2.y);
;         const f32v2 sav = {sa, sa};
;         S01 = S01 * f32v2{wa.x, wa.y} - sav * f32v2{ba.x, ba.y} + vv * bfpair(kq.x);
;         S23 = S23 * f32v2{wa.z, wa.w} - sav * f32v2{ba.z, ba.w} + vv * bfpair(kq.y);
;         S45 = S45 * f32v2{wb.x, wb.y} - sav * f32v2{bbv.x, bbv.y} + vv * bfpair(kq.z);
;         S67 = S67 * f32v2{wb.z, wb.w} - sav * f32v2{bbv.z, bbv.w} + vv * bfpair(kq.w);
;         f32v2 ya = S01 * bfpair(rq.x) + S23 * bfpair(rq.y);
;         f32v2 yb2 = S45 * bfpair(rq.z) + S67 * bfpair(rq.w);
;         ya += yb2;
;         float y = row8_sum(ya.x + ya.y);
;         yd[st * ystride] = y;
	ds_read_b128 v[52:55], v121 offset:15744
	ds_read_b128 v[80:83], v121 offset:16512
	v_pk_mul_f32 v[26:27], v[18:19], v[36:37]
	v_pk_mul_f32 v[30:31], v[18:19], v[72:73]
	v_pk_fma_f32 v[26:27], v[20:21], v[38:39], v[26:27]
	v_pk_fma_f32 v[30:31], v[20:21], v[74:75], v[30:31]
	v_add_f32_e32 v28, v26, v27
	v_add_f32_e32 v32, v30, v31
	ds_read_b128 v[64:67], v121 offset:16256
	v_add_f32_dpp v28, v28, v28 quad_perm:[1,0,3,2] row_mask:0xf bank_mask:0xf bound_ctrl:1
	v_add_f32_dpp v32, v32, v32 quad_perm:[1,0,3,2] row_mask:0xf bank_mask:0xf bound_ctrl:1
	ds_read_u16_d16_hi v70, v122 offset:16768
	v_add_f32_dpp v28, v28, v28 quad_perm:[2,3,0,1] row_mask:0xf bank_mask:0xf bound_ctrl:1
	v_add_f32_dpp v32, v32, v32 quad_perm:[2,3,0,1] row_mask:0xf bank_mask:0xf bound_ctrl:1
	ds_read_b128 v[56:59], v121 offset:15488
	v_add_f32_dpp v28, v28, v28 row_half_mirror row_mask:0xf bank_mask:0xf bound_ctrl:1
	v_add_f32_dpp v32, v32, v32 row_half_mirror row_mask:0xf bank_mask:0xf bound_ctrl:1
	ds_read_b128 v[60:63], v121 offset:16000
	v_add_f32_dpp v28, v28, v28 row_mirror row_mask:0xf bank_mask:0xf bound_ctrl:1
	v_add_f32_dpp v32, v32, v32 row_mirror row_mask:0xf bank_mask:0xf bound_ctrl:1
	v_pk_mul_f32 v[34:35], v[68:69], v[48:49] op_sel_hi:[0,1]
	v_pk_mul_f32 v[112:113], v[68:69], v[50:51] op_sel_hi:[0,1]
	v_pk_fma_f32 v[22:23], v[18:19], v[40:41], v[34:35]
	v_pk_fma_f32 v[24:25], v[20:21], v[42:43], v[112:113]
	v_pk_fma_f32 v[18:19], v[28:29], v[44:45], v[22:23] op_sel_hi:[0,1,1] neg_lo:[1,0,0] neg_hi:[1,0,0]
	v_pk_fma_f32 v[20:21], v[28:29], v[46:47], v[24:25] op_sel_hi:[0,1,1] neg_lo:[1,0,0] neg_hi:[1,0,0]
	ds_write_b32 v148, v32 offset:1152
	s_waitcnt lgkmcnt(1)
	ds_read_b128 v[36:39], v121 offset:17152
	ds_read_b128 v[72:75], v121 offset:17920
	v_pk_mul_f32 v[26:27], v[18:19], v[52:53]
	v_pk_mul_f32 v[30:31], v[18:19], v[76:77]
	v_pk_fma_f32 v[26:27], v[20:21], v[54:55], v[26:27]
	v_pk_fma_f32 v[30:31], v[20:21], v[78:79], v[30:31]
	v_add_f32_e32 v28, v26, v27
	v_add_f32_e32 v32, v30, v31
	ds_read_b128 v[48:51], v121 offset:17664
	v_add_f32_dpp v28, v28, v28 quad_perm:[1,0,3,2] row_mask:0xf bank_mask:0xf bound_ctrl:1
	v_add_f32_dpp v32, v32, v32 quad_perm:[1,0,3,2] row_mask:0xf bank_mask:0xf bound_ctrl:1
	ds_read_u16_d16_hi v68, v122 offset:18176
	v_add_f32_dpp v28, v28, v28 quad_perm:[2,3,0,1] row_mask:0xf bank_mask:0xf bound_ctrl:1
	v_add_f32_dpp v32, v32, v32 quad_perm:[2,3,0,1] row_mask:0xf bank_mask:0xf bound_ctrl:1
	ds_read_b128 v[40:43], v121 offset:16896
	v_add_f32_dpp v28, v28, v28 row_half_mirror row_mask:0xf bank_mask:0xf bound_ctrl:1
	v_add_f32_dpp v32, v32, v32 row_half_mirror row_mask:0xf bank_mask:0xf bound_ctrl:1
	ds_read_b128 v[44:47], v121 offset:17408
	v_add_f32_dpp v28, v28, v28 row_mirror row_mask:0xf bank_mask:0xf bound_ctrl:1
	v_add_f32_dpp v32, v32, v32 row_mirror row_mask:0xf bank_mask:0xf bound_ctrl:1
	v_pk_mul_f32 v[34:35], v[70:71], v[64:65] op_sel_hi:[0,1]
	v_pk_mul_f32 v[112:113], v[70:71], v[66:67] op_sel_hi:[0,1]
	v_pk_fma_f32 v[22:23], v[18:19], v[56:57], v[34:35]
	v_pk_fma_f32 v[24:25], v[20:21], v[58:59], v[112:113]
	v_pk_fma_f32 v[18:19], v[28:29], v[60:61], v[22:23] op_sel_hi:[0,1,1] neg_lo:[1,0,0] neg_hi:[1,0,0]
	v_pk_fma_f32 v[20:21], v[28:29], v[62:63], v[24:25] op_sel_hi:[0,1,1] neg_lo:[1,0,0] neg_hi:[1,0,0]
	ds_write_b32 v148, v32 offset:1280
	s_waitcnt lgkmcnt(1)
	ds_read_b128 v[52:55], v121 offset:18560
	ds_read_b128 v[76:79], v121 offset:19328
	v_pk_mul_f32 v[26:27], v[18:19], v[36:37]
	v_pk_mul_f32 v[30:31], v[18:19], v[80:81]
	v_pk_fma_f32 v[26:27], v[20:21], v[38:39], v[26:27]
	v_pk_fma_f32 v[30:31], v[20:21], v[82:83], v[30:31]
	v_add_f32_e32 v28, v26, v27
	v_add_f32_e32 v32, v30, v31
	ds_read_b128 v[64:67], v121 offset:19072
	v_add_f32_dpp v28, v28, v28 quad_perm:[1,0,3,2] row_mask:0xf bank_mask:0xf bound_ctrl:1
	v_add_f32_dpp v32, v32, v32 quad_perm:[1,0,3,2] row_mask:0xf bank_mask:0xf bound_ctrl:1
	ds_read_u16_d16_hi v70, v122 offset:19584
	v_add_f32_dpp v28, v28, v28 quad_perm:[2,3,0,1] row_mask:0xf bank_mask:0xf bound_ctrl:1
	v_add_f32_dpp v32, v32, v32 quad_perm:[2,3,0,1] row_mask:0xf bank_mask:0xf bound_ctrl:1
	ds_read_b128 v[56:59], v121 offset:18304
	v_add_f32_dpp v28, v28, v28 row_half_mirror row_mask:0xf bank_mask:0xf bound_ctrl:1
	v_add_f32_dpp v32, v32, v32 row_half_mirror row_mask:0xf bank_mask:0xf bound_ctrl:1
	ds_read_b128 v[60:63], v121 offset:18816
	v_add_f32_dpp v28, v28, v28 row_mirror row_mask:0xf bank_mask:0xf bound_ctrl:1
	v_add_f32_dpp v32, v32, v32 row_mirror row_mask:0xf bank_mask:0xf bound_ctrl:1
	v_pk_mul_f32 v[34:35], v[68:69], v[48:49] op_sel_hi:[0,1]
	v_pk_mul_f32 v[112:113], v[68:69], v[50:51] op_sel_hi:[0,1]
	v_pk_fma_f32 v[22:23], v[18:19], v[40:41], v[34:35]
	v_pk_fma_f32 v[24:25], v[20:21], v[42:43], v[112:113]
	v_pk_fma_f32 v[18:19], v[28:29], v[44:45], v[22:23] op_sel_hi:[0,1,1] neg_lo:[1,0,0] neg_hi:[1,0,0]
	v_pk_fma_f32 v[20:21], v[28:29], v[46:47], v[24:25] op_sel_hi:[0,1,1] neg_lo:[1,0,0] neg_hi:[1,0,0]
	ds_write_b32 v148, v32 offset:1408
	s_waitcnt lgkmcnt(1)
; DI f32v2 bfpair(unsigned q) { f32v2 r; r.x = __uint_as_float(q << 16); r.y = __uint_as_float(q & 0xffff0000u); return r; }
; DI void rwkv_scan_item(const PRef& p, int b, int h, int half) {
;     ...
;       for (int st = 0; st < 16; ++st) {
;         float4 wan, wbn, kan, kbn, ban, bbn; uint4 kqn, rqn; unsigned vqn;
;         if (st < 15) {
;           const char* sn = cb + (st + 1) * 1152;
;           wan = *reinterpret_cast<const float4*>(sn + ks * 4); wbn = *reinterpret_cast<const float4*>(sn + ks * 4 + 16);
;           kan = *reinterpret_cast<const float4*>(sn + 256 + ks * 4); kbn = *reinterpret_cast<const float4*>(sn + 256 + ks * 4 + 16);
;           ban = *reinterpret_cast<const float4*>(sn + 512 + ks * 4); bbn = *reinterpret_cast<const float4*>(sn + 512 + ks * 4 + 16);
;           kqn = *reinterpret_cast<const uint4*>(sn + 768 + ks * 2);
;           rqn = *reinterpret_cast<const uint4*>(sn + 896 + ks * 2);
;           vqn = *reinterpret_cast<const u16*>(sn + 1024 + row * 2);
;         }
;         const float v = __uint_as_float(vq << 16);
;         const f32v2 vv = {v, v};
;         const f32v2 kk01 = {ka.x, ka.y}, kk23 = {ka.z, ka.w}, kk45 = {kb.x, kb.y}, kk67 = {kb.z, kb.w};
;         f32v2 sa2 = S01 * kk01 + S23 * kk23;
;         f32v2 sb2 = S45 * kk45 + S67 * kk67;
;         sa2 += sb2;
;         float sa = row8_sum(sa2.x + sa2.y);
;         const f32v2 sav = {sa, sa};
;         S01 = S01 * f32v2{wa.x, wa.y} - sav * f32v2{ba.x, ba.y} + vv * bfpair(kq.x);
;         S23 = S23 * f32v2{wa.z, wa.w} - sav * f32v2{ba.z, ba.w} + vv * bfpair(kq.y);
;         S45 = S45 * f32v2{wb.x, wb.y} - sav * f32v2{bbv.x, bbv.y} + vv * bfpair(kq.z);
;         S67 = S67 * f32v2{wb.z, wb.w} - sav * f32v2{bbv.z, bbv.w} + vv * bfpair(kq.w);
;         f32v2 ya = S01 * bfpair(rq.x) + S23 * bfpair(rq.y);
;         f32v2 yb2 = S45 * bfpair(rq.z) + S67 * bfpair(rq.w);
;         ya += yb2;
;         float y = row8_sum(ya.x + ya.y);
;         yd[st * ystride] = y;
;         if (st < 15) { wa = wan; wb = wbn; ka = kan; kb = kbn; ba = ban; bbv = bbn; kq = kqn; rq = rqn; vq = vqn; }
;       }
;     }
;   }
	ds_read_b128 v[36:39], v121 offset:19968
	ds_read_b128 v[80:83], v121 offset:20736
	v_pk_mul_f32 v[26:27], v[18:19], v[52:53]
	v_pk_mul_f32 v[30:31], v[18:19], v[72:73]
	v_pk_fma_f32 v[26:27], v[20:21], v[54:55], v[26:27]
	v_pk_fma_f32 v[30:31], v[20:21], v[74:75], v[30:31]
	v_add_f32_e32 v28, v26, v27
	v_add_f32_e32 v32, v30, v31
	ds_read_b128 v[48:51], v121 offset:20480
	v_add_f32_dpp v28, v28, v28 quad_perm:[1,0,3,2] row_mask:0xf bank_mask:0xf bound_ctrl:1
	v_add_f32_dpp v32, v32, v32 quad_perm:[1,0,3,2] row_mask:0xf bank_mask:0xf bound_ctrl:1
	ds_read_u16_d16_hi v68, v122 offset:20992
	v_add_f32_dpp v28, v28, v28 quad_perm:[2,3,0,1] row_mask:0xf bank_mask:0xf bound_ctrl:1
	v_add_f32_dpp v32, v32, v32 quad_perm:[2,3,0,1] row_mask:0xf bank_mask:0xf bound_ctrl:1
	ds_read_b128 v[40:43], v121 offset:19712
	v_add_f32_dpp v28, v28, v28 row_half_mirror row_mask:0xf bank_mask:0xf bound_ctrl:1
	v_add_f32_dpp v32, v32, v32 row_half_mirror row_mask:0xf bank_mask:0xf bound_ctrl:1
	ds_read_b128 v[44:47], v121 offset:20224
	v_add_f32_dpp v28, v28, v28 row_mirror row_mask:0xf bank_mask:0xf bound_ctrl:1
	v_add_f32_dpp v32, v32, v32 row_mirror row_mask:0xf bank_mask:0xf bound_ctrl:1
	v_pk_mul_f32 v[34:35], v[70:71], v[64:65] op_sel_hi:[0,1]
	v_pk_mul_f32 v[112:113], v[70:71], v[66:67] op_sel_hi:[0,1]
	v_pk_fma_f32 v[22:23], v[18:19], v[56:57], v[34:35]
	v_pk_fma_f32 v[24:25], v[20:21], v[58:59], v[112:113]
	v_pk_fma_f32 v[18:19], v[28:29], v[60:61], v[22:23] op_sel_hi:[0,1,1] neg_lo:[1,0,0] neg_hi:[1,0,0]
	v_pk_fma_f32 v[20:21], v[28:29], v[62:63], v[24:25] op_sel_hi:[0,1,1] neg_lo:[1,0,0] neg_hi:[1,0,0]
	ds_write_b32 v148, v32 offset:1536
	s_waitcnt lgkmcnt(1)
	ds_read_b128 v[52:55], v121 offset:21376
	ds_read_b128 v[72:75], v121 offset:22144
	v_pk_mul_f32 v[26:27], v[18:19], v[36:37]
	v_pk_mul_f32 v[30:31], v[18:19], v[76:77]
	v_pk_fma_f32 v[26:27], v[20:21], v[38:39], v[26:27]
	v_pk_fma_f32 v[30:31], v[20:21], v[78:79], v[30:31]
	v_add_f32_e32 v28, v26, v27
	v_add_f32_e32 v32, v30, v31
	ds_read_b128 v[64:67], v121 offset:21888
	v_add_f32_dpp v28, v28, v28 quad_perm:[1,0,3,2] row_mask:0xf bank_mask:0xf bound_ctrl:1
	v_add_f32_dpp v32, v32, v32 quad_perm:[1,0,3,2] row_mask:0xf bank_mask:0xf bound_ctrl:1
	ds_read_u16_d16_hi v70, v122 offset:22400
	v_add_f32_dpp v28, v28, v28 quad_perm:[2,3,0,1] row_mask:0xf bank_mask:0xf bound_ctrl:1
	v_add_f32_dpp v32, v32, v32 quad_perm:[2,3,0,1] row_mask:0xf bank_mask:0xf bound_ctrl:1
	ds_read_b128 v[56:59], v121 offset:21120
	v_add_f32_dpp v28, v28, v28 row_half_mirror row_mask:0xf bank_mask:0xf bound_ctrl:1
	v_add_f32_dpp v32, v32, v32 row_half_mirror row_mask:0xf bank_mask:0xf bound_ctrl:1
	ds_read_b128 v[60:63], v121 offset:21632
	v_add_f32_dpp v28, v28, v28 row_mirror row_mask:0xf bank_mask:0xf bound_ctrl:1
	v_add_f32_dpp v32, v32, v32 row_mirror row_mask:0xf bank_mask:0xf bound_ctrl:1
	v_pk_mul_f32 v[34:35], v[68:69], v[48:49] op_sel_hi:[0,1]
	v_pk_mul_f32 v[112:113], v[68:69], v[50:51] op_sel_hi:[0,1]
	v_pk_fma_f32 v[22:23], v[18:19], v[40:41], v[34:35]
	v_pk_fma_f32 v[24:25], v[20:21], v[42:43], v[112:113]
	v_pk_fma_f32 v[18:19], v[28:29], v[44:45], v[22:23] op_sel_hi:[0,1,1] neg_lo:[1,0,0] neg_hi:[1,0,0]
	v_pk_fma_f32 v[20:21], v[28:29], v[46:47], v[24:25] op_sel_hi:[0,1,1] neg_lo:[1,0,0] neg_hi:[1,0,0]
	ds_write_b32 v148, v32 offset:1664
	s_waitcnt lgkmcnt(1)
	v_pk_mul_f32 v[26:27], v[18:19], v[52:53]
	v_pk_mul_f32 v[30:31], v[18:19], v[80:81]
	v_pk_fma_f32 v[26:27], v[20:21], v[54:55], v[26:27]
	v_pk_fma_f32 v[30:31], v[20:21], v[82:83], v[30:31]
	v_add_f32_e32 v28, v26, v27
	v_add_f32_e32 v32, v30, v31
	v_pk_mul_f32 v[34:35], v[70:71], v[64:65] op_sel_hi:[0,1]
	v_add_f32_dpp v28, v28, v28 quad_perm:[1,0,3,2] row_mask:0xf bank_mask:0xf bound_ctrl:1
	v_add_f32_dpp v32, v32, v32 quad_perm:[1,0,3,2] row_mask:0xf bank_mask:0xf bound_ctrl:1
	v_pk_mul_f32 v[112:113], v[70:71], v[66:67] op_sel_hi:[0,1]
	v_add_f32_dpp v28, v28, v28 quad_perm:[2,3,0,1] row_mask:0xf bank_mask:0xf bound_ctrl:1
	v_add_f32_dpp v32, v32, v32 quad_perm:[2,3,0,1] row_mask:0xf bank_mask:0xf bound_ctrl:1
	s_nop 0
	v_add_f32_dpp v28, v28, v28 row_half_mirror row_mask:0xf bank_mask:0xf bound_ctrl:1
	v_add_f32_dpp v32, v32, v32 row_half_mirror row_mask:0xf bank_mask:0xf bound_ctrl:1
	s_nop 0
	v_add_f32_dpp v28, v28, v28 row_mirror row_mask:0xf bank_mask:0xf bound_ctrl:1
	v_add_f32_dpp v32, v32, v32 row_mirror row_mask:0xf bank_mask:0xf bound_ctrl:1
	v_pk_fma_f32 v[22:23], v[18:19], v[56:57], v[34:35]
	v_pk_fma_f32 v[24:25], v[20:21], v[58:59], v[112:113]
	v_pk_fma_f32 v[18:19], v[28:29], v[60:61], v[22:23] op_sel_hi:[0,1,1] neg_lo:[1,0,0] neg_hi:[1,0,0]
	v_pk_fma_f32 v[20:21], v[28:29], v[62:63], v[24:25] op_sel_hi:[0,1,1] neg_lo:[1,0,0] neg_hi:[1,0,0]
	ds_write_b32 v148, v32 offset:1792
	v_pk_mul_f32 v[30:31], v[18:19], v[72:73]
	s_nop 0
	v_pk_fma_f32 v[30:31], v[20:21], v[74:75], v[30:31]
	s_nop 0
	v_add_f32_e32 v32, v30, v31
	s_nop 1
	v_add_f32_dpp v32, v32, v32 quad_perm:[1,0,3,2] row_mask:0xf bank_mask:0xf bound_ctrl:1
	s_nop 1
	v_add_f32_dpp v32, v32, v32 quad_perm:[2,3,0,1] row_mask:0xf bank_mask:0xf bound_ctrl:1
	s_nop 1
	v_add_f32_dpp v32, v32, v32 row_half_mirror row_mask:0xf bank_mask:0xf bound_ctrl:1
	s_nop 1
	v_add_f32_dpp v32, v32, v32 row_mirror row_mask:0xf bank_mask:0xf bound_ctrl:1
	ds_write_b32 v148, v32 offset:1920
	v_add_u32_e32 v100, 16, v100
	s_add_u32 s14, s14, 0x9000
	s_addc_u32 s15, s15, 0
	s_add_i32 s27, s27, 2
	s_cmp_lg_u32 s27, 0x100
	s_cbranch_scc1 .Lrw_loop
	s_branch .LBB0_185

; DI unsigned pack2(float a, float b) { f32v2 v = {a, b}; return __builtin_bit_cast(unsigned, __builtin_convertvector(v, bf16v2)); }
;     ...
; #pragma unroll
;     for (int r = 0; r < 2; ++r) {
;       const int e = tid + r * 512, i = e >> 4, j4 = (e & 15) * 4;
;       float4 v = make_float4(0.f, 0.f, 0.f, 0.f);
;       const int sn0 = upmap ? ((n0 & 255) >> 7) * DFF + (n0 >> 8) * 128 + (n0 & 127) : n0;
;       if (n0 + j4 < N) v = *reinterpret_cast<const float4*>(src + (size_t)(k0 + i) * N + sn0 + j4);
;       tile[i * 65 + j4] = v.x; tile[i * 65 + j4 + 1] = v.y; tile[i * 65 + j4 + 2] = v.z; tile[i * 65 + j4 + 3] = v.w;
;     }
;     __syncthreads();
;     {
;       const int jn = tid >> 3, seg = tid & 7;
;       const float* tp = tile + (seg * 8) * 65 + jn;
;       uint4 o;
;       o.x = pack2(tp[0], tp[65]); o.y = pack2(tp[2 * 65], tp[3 * 65]); o.z = pack2(tp[4 * 65], tp[5 * 65]); o.w = pack2(tp[6 * 65], tp[7 * 65]);
.LBB0_1131:
	s_or_b64 exec, exec, s[10:11]
	v_lshl_add_u32 v6, v7, 2, 16
	v_mad_u64_u32 v[10:11], s[10:11], v1, s47, v[6:7]
	v_add_u32_e32 v1, 0x200, v8
	v_ashrrev_i32_e32 v24, 4, v1
	v_mov_b32_e32 v20, 0
	v_mov_b32_e32 v21, 0
	v_mov_b32_e32 v22, 0
	v_mov_b32_e32 v23, 0
	s_and_saveexec_b64 s[10:11], vcc
	s_cbranch_execz .LBB0_1133
	s_lshl_b32 s9, s15, 10
	v_subrev_u32_e32 v20, s9, v24
	v_add_u32_e32 v22, s13, v20
	v_mov_b64_e32 v[20:21], s[4:5]
	s_movk_i32 s9, 0x2a00
	v_mad_i64_i32 v[20:21], s[16:17], v22, s9, v[20:21]
	s_ashr_i32 s9, s8, 31
	v_lshl_add_u64 v[20:21], s[8:9], 2, v[20:21]
	v_lshlrev_b32_e32 v16, 2, v7
	v_lshl_add_u64 v[20:21], v[20:21], 0, v[16:17]
	global_load_dwordx4 v[20:23], v[20:21], off
.LBB0_1133:
	s_or_b64 exec, exec, s[10:11]
	s_waitcnt vmcnt(1)
	ds_write2_b32 v10, v2, v3 offset1:1
	ds_write2_b32 v10, v4, v5 offset0:2 offset1:3
	v_mad_u64_u32 v[4:5], s[10:11], v24, s47, v[6:7]
	s_waitcnt vmcnt(0)
	ds_write2_b32 v4, v20, v21 offset1:1
	ds_write2_b32 v4, v22, v23 offset0:2 offset1:3
	v_lshlrev_b32_e32 v0, 3, v8
	v_ashrrev_i32_e32 v10, 3, v8
	v_and_b32_e32 v9, 56, v0
	v_mul_u32_u24_e32 v0, 0x104, v9
	v_lshlrev_b32_e32 v1, 2, v10
	v_add3_u32 v4, 16, v0, v1
	v_add_u32_e32 v6, 0x400, v4
	s_waitcnt lgkmcnt(0)
	s_barrier
	ds_read2_b32 v[0:1], v4 offset1:65
	ds_read2_b32 v[2:3], v4 offset0:130 offset1:195
	ds_read2_b32 v[4:5], v6 offset0:4 offset1:69
	ds_read2_b32 v[6:7], v6 offset0:134 offset1:199
	s_cmpk_gt_i32 s12, 0xff
	s_cbranch_scc1 .LBB0_1128
	v_lshrrev_b32_e32 v11, 3, v8
	v_lshrrev_b32_e32 v12, 2, v8
	v_ashrrev_i32_e32 v8, 6, v8
	v_and_b32_e32 v12, 32, v12
	v_and_b32_e32 v8, -4, v8
	v_lshlrev_b32_e32 v10, 1, v10
	v_add_u32_e32 v8, v8, v12
	v_and_b32_e32 v10, 24, v10
	v_and_or_b32 v8, v11, 3, v8
	v_add_u32_e32 v10, v8, v10
	s_branch .LBB0_1128

;     ...
; #pragma unroll
;     for (int r = 0; r < 2; ++r) {
;       const int e = tid + r * 512, i = e >> 4, j4 = (e & 15) * 4;
;       float4 v = make_float4(0.f, 0.f, 0.f, 0.f);
;       const int sn0 = upmap ? ((n0 & 255) >> 7) * DFF + (n0 >> 8) * 128 + (n0 & 127) : n0;
;       if (n0 + j4 < N) v = *reinterpret_cast<const float4*>(src + (size_t)(k0 + i) * N + sn0 + j4);
;       tile[i * 65 + j4] = v.x; tile[i * 65 + j4 + 1] = v.y; tile[i * 65 + j4 + 2] = v.z; tile[i * 65 + j4 + 3] = v.w;
;     }
;     __syncthreads();
.LBB0_1142:
	s_or_b64 exec, exec, s[12:13]
	v_lshl_add_u32 v6, v7, 2, 16
	v_mad_u64_u32 v[10:11], s[12:13], v1, s47, v[6:7]
	v_add_u32_e32 v1, 0x200, v8
	v_ashrrev_i32_e32 v24, 4, v1
	v_mov_b32_e32 v20, 0
	v_mov_b32_e32 v21, 0
	v_mov_b32_e32 v22, 0
	v_mov_b32_e32 v23, 0
	s_and_saveexec_b64 s[12:13], vcc
	s_cbranch_execz .LBB0_1144
	v_add_u32_e32 v20, s8, v24
	v_ashrrev_i32_e32 v21, 31, v20
	v_lshlrev_b64 v[20:21], 12, v[20:21]
	v_lshl_add_u64 v[20:21], s[4:5], 0, v[20:21]
	s_ashr_i32 s11, s10, 31
	v_lshl_add_u64 v[20:21], s[10:11], 2, v[20:21]
	v_lshlrev_b32_e32 v16, 2, v7
	v_lshl_add_u64 v[20:21], v[20:21], 0, v[16:17]
	global_load_dwordx4 v[20:23], v[20:21], off
.LBB0_1144:
	s_or_b64 exec, exec, s[12:13]
	s_waitcnt vmcnt(1)
	ds_write2_b32 v10, v2, v3 offset1:1
	ds_write2_b32 v10, v4, v5 offset0:2 offset1:3
	v_mad_u64_u32 v[4:5], s[12:13], v24, s47, v[6:7]
	s_waitcnt vmcnt(0)
	ds_write2_b32 v4, v20, v21 offset1:1
	ds_write2_b32 v4, v22, v23 offset0:2 offset1:3
	v_lshlrev_b32_e32 v0, 3, v8
	v_ashrrev_i32_e32 v10, 3, v8
	v_and_b32_e32 v9, 56, v0
	v_mul_u32_u24_e32 v0, 0x104, v9
	v_lshlrev_b32_e32 v1, 2, v10
	v_add3_u32 v4, 16, v0, v1
	v_add_u32_e32 v6, 0x400, v4
	s_waitcnt lgkmcnt(0)
	s_barrier
	ds_read2_b32 v[0:1], v4 offset1:65
	ds_read2_b32 v[2:3], v4 offset0:130 offset1:195
	ds_read2_b32 v[4:5], v6 offset0:4 offset1:69
	ds_read2_b32 v[6:7], v6 offset0:134 offset1:199
	s_cmpk_gt_i32 s14, 0x2b0
	s_cbranch_scc1 .LBB0_1139
	v_lshrrev_b32_e32 v11, 3, v8
	v_lshrrev_b32_e32 v12, 2, v8
	v_ashrrev_i32_e32 v8, 6, v8
	v_and_b32_e32 v12, 32, v12
	v_and_b32_e32 v8, -4, v8
	v_lshlrev_b32_e32 v10, 1, v10
	v_add_u32_e32 v8, v8, v12
	v_and_b32_e32 v10, 24, v10
	v_and_or_b32 v8, v11, 3, v8
	v_add_u32_e32 v10, v8, v10
	s_branch .LBB0_1139

;     ...
; #pragma unroll
;     for (int r = 0; r < 2; ++r) {
;       const int e = tid + r * 512, i = e >> 4, j4 = (e & 15) * 4;
;       float4 v = make_float4(0.f, 0.f, 0.f, 0.f);
;       const int sn0 = upmap ? ((n0 & 255) >> 7) * DFF + (n0 >> 8) * 128 + (n0 & 127) : n0;
;       if (n0 + j4 < N) v = *reinterpret_cast<const float4*>(src + (size_t)(k0 + i) * N + sn0 + j4);
;       tile[i * 65 + j4] = v.x; tile[i * 65 + j4 + 1] = v.y; tile[i * 65 + j4 + 2] = v.z; tile[i * 65 + j4 + 3] = v.w;
;     }
;     __syncthreads();
.LBB0_1155:
	s_or_b64 exec, exec, s[12:13]
	s_waitcnt vmcnt(1)
	ds_write2_b32 v10, v2, v3 offset1:1
	ds_write2_b32 v10, v4, v5 offset0:2 offset1:3
	v_mad_u64_u32 v[4:5], s[12:13], v24, s47, v[6:7]
	s_waitcnt vmcnt(0)
	ds_write2_b32 v4, v20, v21 offset1:1
	ds_write2_b32 v4, v22, v23 offset0:2 offset1:3
	v_lshlrev_b32_e32 v0, 3, v8
	v_ashrrev_i32_e32 v10, 3, v8
	v_and_b32_e32 v9, 56, v0
	v_mul_u32_u24_e32 v0, 0x104, v9
	v_lshlrev_b32_e32 v1, 2, v10
	v_add3_u32 v4, 16, v0, v1
	v_add_u32_e32 v6, 0x400, v4
	s_waitcnt lgkmcnt(0)
	s_barrier
	ds_read2_b32 v[0:1], v4 offset1:65
	ds_read2_b32 v[2:3], v4 offset0:130 offset1:195
	ds_read2_b32 v[4:5], v6 offset0:4 offset1:69
	ds_read2_b32 v[6:7], v6 offset0:134 offset1:199
	s_cmpk_gt_i32 s14, 0x3b0
	s_cbranch_scc1 .LBB0_1150
	v_lshrrev_b32_e32 v11, 3, v8
	v_lshrrev_b32_e32 v12, 2, v8
	v_ashrrev_i32_e32 v8, 6, v8
	v_and_b32_e32 v12, 32, v12
	v_and_b32_e32 v8, -4, v8
	v_lshlrev_b32_e32 v10, 1, v10
	v_add_u32_e32 v8, v8, v12
	v_and_b32_e32 v10, 24, v10
	v_and_or_b32 v8, v11, 3, v8
	v_add_u32_e32 v10, v8, v10
	s_branch .LBB0_1150

;     ...
; #pragma unroll
;     for (int r = 0; r < 2; ++r) {
;       const int e = tid + r * 512, i = e >> 4, j4 = (e & 15) * 4;
;       float4 v = make_float4(0.f, 0.f, 0.f, 0.f);
;       const int sn0 = upmap ? ((n0 & 255) >> 7) * DFF + (n0 >> 8) * 128 + (n0 & 127) : n0;
;       if (n0 + j4 < N) v = *reinterpret_cast<const float4*>(src + (size_t)(k0 + i) * N + sn0 + j4);
;       tile[i * 65 + j4] = v.x; tile[i * 65 + j4 + 1] = v.y; tile[i * 65 + j4 + 2] = v.z; tile[i * 65 + j4 + 3] = v.w;
;     }
;     __syncthreads();
.LBB0_1164:
	s_or_b64 exec, exec, s[12:13]
	v_lshl_add_u32 v6, v7, 2, 16
	v_mad_u64_u32 v[10:11], s[12:13], v1, s47, v[6:7]
	v_add_u32_e32 v1, 0x200, v8
	v_ashrrev_i32_e32 v24, 4, v1
	v_mov_b32_e32 v20, 0
	v_mov_b32_e32 v21, 0
	v_mov_b32_e32 v22, 0
	v_mov_b32_e32 v23, 0
	s_and_saveexec_b64 s[12:13], vcc
	s_cbranch_execz .LBB0_1166
	v_add_u32_e32 v20, s8, v24
	v_ashrrev_i32_e32 v21, 31, v20
	v_lshlrev_b64 v[20:21], 13, v[20:21]
	v_lshl_add_u64 v[20:21], s[4:5], 0, v[20:21]
	s_ashr_i32 s11, s10, 31
	v_lshl_add_u64 v[20:21], s[10:11], 2, v[20:21]
	v_lshlrev_b32_e32 v16, 2, v7
	v_lshl_add_u64 v[20:21], v[20:21], 0, v[16:17]
	global_load_dwordx4 v[20:23], v[20:21], off
.LBB0_1166:
	s_or_b64 exec, exec, s[12:13]
	s_waitcnt vmcnt(1)
	ds_write2_b32 v10, v2, v3 offset1:1
	ds_write2_b32 v10, v4, v5 offset0:2 offset1:3
	v_mad_u64_u32 v[4:5], s[12:13], v24, s47, v[6:7]
	s_waitcnt vmcnt(0)
	ds_write2_b32 v4, v20, v21 offset1:1
	ds_write2_b32 v4, v22, v23 offset0:2 offset1:3
	v_lshlrev_b32_e32 v0, 3, v8
	v_ashrrev_i32_e32 v10, 3, v8
	v_and_b32_e32 v9, 56, v0
	v_mul_u32_u24_e32 v0, 0x104, v9
	v_lshlrev_b32_e32 v1, 2, v10
	v_add3_u32 v4, 16, v0, v1
	v_add_u32_e32 v6, 0x400, v4
	s_waitcnt lgkmcnt(0)
	s_barrier
	ds_read2_b32 v[0:1], v4 offset1:65
	ds_read2_b32 v[2:3], v4 offset0:130 offset1:195
	ds_read2_b32 v[4:5], v6 offset0:4 offset1:69
	ds_read2_b32 v[6:7], v6 offset0:134 offset1:199
	s_cmpk_gt_i32 s14, 0x4b0
	s_cbranch_scc1 .LBB0_1161
	v_lshrrev_b32_e32 v11, 3, v8
	v_lshrrev_b32_e32 v12, 2, v8
	v_ashrrev_i32_e32 v8, 6, v8
	v_and_b32_e32 v12, 32, v12
	v_and_b32_e32 v8, -4, v8
	v_lshlrev_b32_e32 v10, 1, v10
	v_add_u32_e32 v8, v8, v12
	v_and_b32_e32 v10, 24, v10
	v_and_or_b32 v8, v11, 3, v8
	v_add_u32_e32 v10, v8, v10
	s_branch .LBB0_1161

;     ...
; #pragma unroll
;     for (int r = 0; r < 2; ++r) {
;       const int e = tid + r * 512, i = e >> 4, j4 = (e & 15) * 4;
;       float4 v = make_float4(0.f, 0.f, 0.f, 0.f);
;       const int sn0 = upmap ? ((n0 & 255) >> 7) * DFF + (n0 >> 8) * 128 + (n0 & 127) : n0;
;       if (n0 + j4 < N) v = *reinterpret_cast<const float4*>(src + (size_t)(k0 + i) * N + sn0 + j4);
;       tile[i * 65 + j4] = v.x; tile[i * 65 + j4 + 1] = v.y; tile[i * 65 + j4 + 2] = v.z; tile[i * 65 + j4 + 3] = v.w;
;     }
;     __syncthreads();
.LBB0_1177:
	s_or_b64 exec, exec, s[12:13]
	s_waitcnt vmcnt(1)
	ds_write2_b32 v10, v2, v3 offset1:1
	ds_write2_b32 v10, v4, v5 offset0:2 offset1:3
	v_mad_u64_u32 v[4:5], s[12:13], v24, s47, v[6:7]
	s_waitcnt vmcnt(0)
	ds_write2_b32 v4, v20, v21 offset1:1
	ds_write2_b32 v4, v22, v23 offset0:2 offset1:3
	v_lshlrev_b32_e32 v0, 3, v8
	v_ashrrev_i32_e32 v10, 3, v8
	v_and_b32_e32 v9, 56, v0
	v_mul_u32_u24_e32 v0, 0x104, v9
	v_lshlrev_b32_e32 v1, 2, v10
	v_add3_u32 v4, 16, v0, v1
	v_add_u32_e32 v6, 0x400, v4
	s_waitcnt lgkmcnt(0)
	s_barrier
	ds_read2_b32 v[0:1], v4 offset1:65
	ds_read2_b32 v[2:3], v4 offset0:130 offset1:195
	ds_read2_b32 v[4:5], v6 offset0:4 offset1:69
	ds_read2_b32 v[6:7], v6 offset0:134 offset1:199
	s_cmpk_gt_i32 s14, 0x6b0
	s_cbranch_scc1 .LBB0_1172
	v_lshrrev_b32_e32 v11, 3, v8
	v_lshrrev_b32_e32 v12, 2, v8
	v_ashrrev_i32_e32 v8, 6, v8
	v_and_b32_e32 v12, 32, v12
	v_and_b32_e32 v8, -4, v8
	v_lshlrev_b32_e32 v10, 1, v10
	v_add_u32_e32 v8, v8, v12
	v_and_b32_e32 v10, 24, v10
	v_and_or_b32 v8, v11, 3, v8
	v_add_u32_e32 v10, v8, v10
	s_branch .LBB0_1172

;     ...
; #pragma unroll
;     for (int r = 0; r < 2; ++r) {
;       const int e = tid + r * 512, i = e >> 4, j4 = (e & 15) * 4;
;       float4 v = make_float4(0.f, 0.f, 0.f, 0.f);
;       const int sn0 = upmap ? ((n0 & 255) >> 7) * DFF + (n0 >> 8) * 128 + (n0 & 127) : n0;
;       if (n0 + j4 < N) v = *reinterpret_cast<const float4*>(src + (size_t)(k0 + i) * N + sn0 + j4);
;       tile[i * 65 + j4] = v.x; tile[i * 65 + j4 + 1] = v.y; tile[i * 65 + j4 + 2] = v.z; tile[i * 65 + j4 + 3] = v.w;
;     }
;     __syncthreads();
.LBB0_1186:
	s_or_b64 exec, exec, s[12:13]
	v_lshl_add_u32 v6, v7, 2, 16
	v_mad_u64_u32 v[10:11], s[12:13], v1, s47, v[6:7]
	v_add_u32_e32 v1, 0x200, v8
	v_ashrrev_i32_e32 v24, 4, v1
	v_mov_b32_e32 v20, 0
	v_mov_b32_e32 v21, 0
	v_mov_b32_e32 v22, 0
	v_mov_b32_e32 v23, 0
	s_and_saveexec_b64 s[12:13], vcc
	s_cbranch_execz .LBB0_1188
	v_add_u32_e32 v22, s8, v24
	v_mov_b64_e32 v[20:21], s[4:5]
	s_movk_i32 s11, 0x5800
	v_mad_i64_i32 v[20:21], s[16:17], v22, s11, v[20:21]
	s_ashr_i32 s11, s10, 31
	v_lshl_add_u64 v[20:21], s[10:11], 2, v[20:21]
	v_lshlrev_b32_e32 v16, 2, v7
	v_lshl_add_u64 v[20:21], v[20:21], 0, v[16:17]
	global_load_dwordx4 v[20:23], v[20:21], off
.LBB0_1188:
	s_or_b64 exec, exec, s[12:13]
	s_waitcnt vmcnt(1)
	ds_write2_b32 v10, v2, v3 offset1:1
	ds_write2_b32 v10, v4, v5 offset0:2 offset1:3
	v_mad_u64_u32 v[4:5], s[10:11], v24, s47, v[6:7]
	s_waitcnt vmcnt(0)
	ds_write2_b32 v4, v20, v21 offset1:1
	ds_write2_b32 v4, v22, v23 offset0:2 offset1:3
	v_lshlrev_b32_e32 v0, 3, v8
	v_ashrrev_i32_e32 v10, 3, v8
	v_and_b32_e32 v9, 56, v0
	v_mul_u32_u24_e32 v0, 0x104, v9
	v_lshlrev_b32_e32 v1, 2, v10
	v_add3_u32 v4, 16, v0, v1
	v_add_u32_e32 v6, 0x400, v4
	s_waitcnt lgkmcnt(0)
	s_barrier
	ds_read2_b32 v[0:1], v4 offset1:65
	ds_read2_b32 v[2:3], v4 offset0:130 offset1:195
	ds_read2_b32 v[4:5], v6 offset0:4 offset1:69
	ds_read2_b32 v[6:7], v6 offset0:134 offset1:199
	s_cmpk_gt_i32 s14, 0x7b0
	s_cbranch_scc1 .LBB0_1183
	v_lshrrev_b32_e32 v11, 3, v8
	v_lshrrev_b32_e32 v12, 2, v8
	v_ashrrev_i32_e32 v8, 6, v8
	v_and_b32_e32 v12, 32, v12
	v_and_b32_e32 v8, -4, v8
	v_lshlrev_b32_e32 v10, 1, v10
	v_add_u32_e32 v8, v8, v12
	v_and_b32_e32 v10, 24, v10
	v_and_or_b32 v8, v11, 3, v8
	v_add_u32_e32 v10, v8, v10
	s_branch .LBB0_1183

;     ...
; #pragma unroll
;     for (int r = 0; r < 2; ++r) {
;       const int e = tid + r * 512, i = e >> 4, j4 = (e & 15) * 4;
;       float4 v = make_float4(0.f, 0.f, 0.f, 0.f);
;       const int sn0 = upmap ? ((n0 & 255) >> 7) * DFF + (n0 >> 8) * 128 + (n0 & 127) : n0;
;       if (n0 + j4 < N) v = *reinterpret_cast<const float4*>(src + (size_t)(k0 + i) * N + sn0 + j4);
;       tile[i * 65 + j4] = v.x; tile[i * 65 + j4 + 1] = v.y; tile[i * 65 + j4 + 2] = v.z; tile[i * 65 + j4 + 3] = v.w;
;     }
;     __syncthreads();
.LBB0_1199:
	s_or_b64 exec, exec, s[12:13]
	s_waitcnt vmcnt(1)
	ds_write2_b32 v10, v2, v3 offset1:1
	ds_write2_b32 v10, v4, v5 offset0:2 offset1:3
	v_mad_u64_u32 v[4:5], s[12:13], v24, s47, v[6:7]
	s_waitcnt vmcnt(0)
	ds_write2_b32 v4, v20, v21 offset1:1
	ds_write2_b32 v4, v22, v23 offset0:2 offset1:3
	v_lshlrev_b32_e32 v0, 3, v8
	v_ashrrev_i32_e32 v10, 3, v8
	v_and_b32_e32 v9, 56, v0
	v_mul_u32_u24_e32 v0, 0x104, v9
	v_lshlrev_b32_e32 v1, 2, v10
	v_add3_u32 v4, 16, v0, v1
	v_add_u32_e32 v6, 0x400, v4
	s_waitcnt lgkmcnt(0)
	s_barrier
	ds_read2_b32 v[0:1], v4 offset1:65
	ds_read2_b32 v[2:3], v4 offset0:130 offset1:195
	ds_read2_b32 v[4:5], v6 offset0:4 offset1:69
	ds_read2_b32 v[6:7], v6 offset0:134 offset1:199
	s_cmpk_gt_i32 s14, 0xd14
	s_cbranch_scc1 .LBB0_1194
	v_lshrrev_b32_e32 v11, 3, v8
	v_lshrrev_b32_e32 v12, 2, v8
	v_ashrrev_i32_e32 v8, 6, v8
	v_and_b32_e32 v12, 32, v12
	v_and_b32_e32 v8, -4, v8
	v_lshlrev_b32_e32 v10, 1, v10
	v_add_u32_e32 v8, v8, v12
	v_and_b32_e32 v10, 24, v10
	v_and_or_b32 v8, v11, 3, v8
	v_add_u32_e32 v10, v8, v10
	s_branch .LBB0_1194

;     ...
; #pragma unroll
;     for (int r = 0; r < 2; ++r) {
;       const int e = tid + r * 512, i = e >> 4, j4 = (e & 15) * 4;
;       float4 v = make_float4(0.f, 0.f, 0.f, 0.f);
;       const int sn0 = upmap ? ((n0 & 255) >> 7) * DFF + (n0 >> 8) * 128 + (n0 & 127) : n0;
;       if (n0 + j4 < N) v = *reinterpret_cast<const float4*>(src + (size_t)(k0 + i) * N + sn0 + j4);
;       tile[i * 65 + j4] = v.x; tile[i * 65 + j4 + 1] = v.y; tile[i * 65 + j4 + 2] = v.z; tile[i * 65 + j4 + 3] = v.w;
;     }
;     __syncthreads();
.LBB0_1208:
	s_or_b64 exec, exec, s[12:13]
	v_lshl_add_u32 v6, v7, 2, 16
	v_mad_u64_u32 v[10:11], s[12:13], v1, s47, v[6:7]
	v_add_u32_e32 v1, 0x200, v8
	v_ashrrev_i32_e32 v24, 4, v1
	v_mov_b32_e32 v20, 0
	v_mov_b32_e32 v21, 0
	v_mov_b32_e32 v22, 0
	v_mov_b32_e32 v23, 0
	s_and_saveexec_b64 s[12:13], vcc
	s_cbranch_execz .LBB0_1210
	v_add_u32_e32 v20, s8, v24
	v_ashrrev_i32_e32 v21, 31, v20
	v_lshlrev_b64 v[20:21], 10, v[20:21]
	v_lshl_add_u64 v[20:21], s[4:5], 0, v[20:21]
	s_ashr_i32 s11, s10, 31
	v_lshl_add_u64 v[20:21], s[10:11], 2, v[20:21]
	v_lshlrev_b32_e32 v16, 2, v7
	v_lshl_add_u64 v[20:21], v[20:21], 0, v[16:17]
	global_load_dwordx4 v[20:23], v[20:21], off
.LBB0_1210:
	s_or_b64 exec, exec, s[12:13]
	s_waitcnt vmcnt(1)
	ds_write2_b32 v10, v2, v3 offset1:1
	ds_write2_b32 v10, v4, v5 offset0:2 offset1:3
	v_mad_u64_u32 v[4:5], s[12:13], v24, s47, v[6:7]
	s_waitcnt vmcnt(0)
	ds_write2_b32 v4, v20, v21 offset1:1
	ds_write2_b32 v4, v22, v23 offset0:2 offset1:3
	v_lshlrev_b32_e32 v0, 3, v8
	v_ashrrev_i32_e32 v10, 3, v8
	v_and_b32_e32 v9, 56, v0
	v_mul_u32_u24_e32 v0, 0x104, v9
	v_lshlrev_b32_e32 v1, 2, v10
	v_add3_u32 v4, 16, v0, v1
	v_add_u32_e32 v6, 0x400, v4
	s_waitcnt lgkmcnt(0)
	s_barrier
	ds_read2_b32 v[0:1], v4 offset1:65
	ds_read2_b32 v[2:3], v4 offset0:130 offset1:195
	ds_read2_b32 v[4:5], v6 offset0:4 offset1:69
	ds_read2_b32 v[6:7], v6 offset0:134 offset1:199
	s_cmpk_gt_i32 s14, 0xffc
	s_cbranch_scc1 .LBB0_1205
	v_lshrrev_b32_e32 v11, 3, v8
	v_lshrrev_b32_e32 v12, 2, v8
	v_ashrrev_i32_e32 v8, 6, v8
	v_and_b32_e32 v12, 32, v12
	v_and_b32_e32 v8, -4, v8
	v_lshlrev_b32_e32 v10, 1, v10
	v_add_u32_e32 v8, v8, v12
	v_and_b32_e32 v10, 24, v10
	v_and_or_b32 v8, v11, 3, v8
	v_add_u32_e32 v10, v8, v10
	s_branch .LBB0_1205
